# v027 plus: p1_rows parameter loads hoisted per block, spatial gate-row loads issued together, redundant setprio/lgkmcnt removed from K-loop MFMA sections
# speedup vs baseline: 1.0058x; 1.0058x over previous
.LBB0_131:
	v_lshl_add_u64 v[0:1], s[18:19], 0, v[32:33]
	v_mov_b64_e32 v[2:3], s[2:3]
	v_mad_u64_u32 v[8:9], s[6:7], v0, s73, v[2:3]
	v_mov_b32_e32 v0, v9
	v_mad_u64_u32 v[0:1], s[6:7], v1, s73, v[0:1]
	v_mov_b32_e32 v9, v0
	s_mov_b64 s[6:7], 0x1000
	v_lshl_add_u64 v[12:13], v[8:9], 0, s[6:7]
	v_lshl_add_u64 v[4:5], v[12:13], 0, v[192:193]
	global_load_dwordx4 v[0:3], v[58:59], off
	v_lshl_add_u64 v[14:15], v[8:9], 0, v[192:193]
	global_load_dwordx4 v[4:7], v[4:5], off
	v_mov_b32_e32 v34, v25
	global_load_dwordx4 v[8:11], v[14:15], off
	v_lshl_add_u64 v[154:155], v[12:13], 0, v[192:193]
	global_load_dwordx4 v[118:121], v[58:59], off offset:1024
	global_load_dwordx4 v[122:125], v[154:155], off offset:1024
	global_load_dwordx4 v[126:129], v[14:15], off offset:1024
	global_load_dwordx4 v[130:133], v[58:59], off offset:2048
	global_load_dwordx4 v[134:137], v[154:155], off offset:2048
	global_load_dwordx4 v[138:141], v[14:15], off offset:2048
	global_load_dwordx4 v[142:145], v[58:59], off offset:3072
	global_load_dwordx4 v[146:149], v[154:155], off offset:3072
	global_load_dwordx4 v[150:153], v[14:15], off offset:3072
	v_mov_b32_e32 v35, v29
	v_mov_b32_e32 v32, v24
	v_mov_b32_e32 v33, v28
	v_pk_mul_f32 v[34:35], v[34:35], v[34:35]
	v_mov_b32_e32 v36, v21
	v_pk_fma_f32 v[32:33], v[32:33], v[32:33], v[34:35]
	v_mov_b32_e32 v34, v26
	v_mov_b32_e32 v35, v30
	v_pk_fma_f32 v[32:33], v[34:35], v[34:35], v[32:33]
	v_mov_b32_e32 v34, v27
	v_mov_b32_e32 v35, v31
	v_mov_b32_e32 v37, v17
	v_pk_fma_f32 v[32:33], v[34:35], v[34:35], v[32:33]
	v_mov_b32_e32 v34, v20
	v_mov_b32_e32 v35, v16
	v_pk_mul_f32 v[36:37], v[36:37], v[36:37]
	v_add_f32_e32 v32, v32, v33
	v_pk_fma_f32 v[34:35], v[34:35], v[34:35], v[36:37]
	v_mov_b32_e32 v36, v22
	v_mov_b32_e32 v37, v18
	v_pk_fma_f32 v[34:35], v[36:37], v[36:37], v[34:35]
	v_mov_b32_e32 v36, v23
	v_mov_b32_e32 v37, v19
	v_pk_fma_f32 v[34:35], v[36:37], v[36:37], v[34:35]
	s_mov_b32 s6, 0x800000
	v_add_f32_e32 v32, v35, v32
	v_add_f32_e32 v32, v34, v32
	ds_bpermute_b32 v33, v49, v32
	v_mov_b32_e32 v63, v193
	v_mov_b32_e32 v65, v193
	v_mov_b32_e32 v67, v193
	s_waitcnt lgkmcnt(0)
	v_add_f32_e32 v32, v32, v33
	ds_bpermute_b32 v33, v92, v32
	s_waitcnt lgkmcnt(0)
	v_add_f32_e32 v32, v32, v33
	ds_bpermute_b32 v33, v93, v32
	s_waitcnt lgkmcnt(0)
	v_add_f32_e32 v32, v32, v33
	ds_bpermute_b32 v33, v94, v32
	s_waitcnt lgkmcnt(0)
	v_add_f32_e32 v32, v32, v33
	ds_bpermute_b32 v33, v95, v32
	s_waitcnt lgkmcnt(0)
	v_add_f32_e32 v32, v32, v33
	ds_bpermute_b32 v33, v96, v32
	s_waitcnt lgkmcnt(0)
	v_add_f32_e32 v32, v32, v33
	v_fmamk_f32 v32, v32, 0x3a800000, v207
	v_mul_f32_e32 v33, 0x4b800000, v32
	v_cmp_gt_f32_e32 vcc, s6, v32
	s_waitcnt vmcnt(0)
	v_pk_add_f32 v[6:7], v[6:7], 1.0 op_sel_hi:[1,0]
	v_cndmask_b32_e32 v32, v32, v33, vcc
	v_rsq_f32_e32 v34, v32
	v_pk_add_f32 v[4:5], v[4:5], 1.0 op_sel_hi:[1,0]
	v_lshlrev_b64 v[32:33], 11, v[84:85]
	v_lshl_add_u64 v[32:33], v[60:61], 0, v[32:33]
	v_mul_f32_e32 v35, 0x45800000, v34
	v_cndmask_b32_e32 v34, v34, v35, vcc
	v_pk_mul_f32 v[30:31], v[30:31], v[34:35] op_sel_hi:[1,0]
	v_pk_mul_f32 v[28:29], v[28:29], v[34:35] op_sel_hi:[1,0]
	v_pk_mul_f32 v[2:3], v[2:3], v[30:31]
	v_pk_mul_f32 v[0:1], v[0:1], v[28:29]
	v_pk_fma_f32 v[2:3], v[6:7], v[2:3], v[10:11]
	v_pk_fma_f32 v[0:1], v[4:5], v[0:1], v[8:9]
	v_cvt_pk_bf16_f32 v0, v0, v1
	v_cvt_pk_bf16_f32 v1, v2, v3
	global_store_dwordx2 v[32:33], v[0:1], off
	v_pk_mul_f32 v[26:27], v[26:27], v[34:35] op_sel_hi:[1,0]
	v_pk_mul_f32 v[24:25], v[24:25], v[34:35] op_sel_hi:[1,0]
	v_pk_mul_f32 v[18:19], v[18:19], v[34:35] op_sel_hi:[1,0]
	v_pk_mul_f32 v[16:17], v[16:17], v[34:35] op_sel_hi:[1,0]
	v_pk_add_f32 v[6:7], v[124:125], 1.0 op_sel_hi:[1,0]
	v_pk_mul_f32 v[0:1], v[118:119], v[24:25]
	v_pk_mul_f32 v[2:3], v[120:121], v[26:27]
	v_pk_add_f32 v[4:5], v[122:123], 1.0 op_sel_hi:[1,0]
	v_pk_fma_f32 v[2:3], v[6:7], v[2:3], v[128:129]
	v_pk_fma_f32 v[0:1], v[4:5], v[0:1], v[126:127]
	v_cvt_pk_bf16_f32 v0, v0, v1
	v_cvt_pk_bf16_f32 v1, v2, v3
	global_store_dwordx2 v[32:33], v[0:1], off offset:512
	v_pk_add_f32 v[6:7], v[136:137], 1.0 op_sel_hi:[1,0]
	v_pk_mul_f32 v[0:1], v[130:131], v[16:17]
	v_pk_mul_f32 v[2:3], v[132:133], v[18:19]
	v_pk_add_f32 v[4:5], v[134:135], 1.0 op_sel_hi:[1,0]
	v_pk_fma_f32 v[2:3], v[6:7], v[2:3], v[140:141]
	v_pk_fma_f32 v[0:1], v[4:5], v[0:1], v[138:139]
	v_cvt_pk_bf16_f32 v0, v0, v1
	v_cvt_pk_bf16_f32 v1, v2, v3
	global_store_dwordx2 v[32:33], v[0:1], off offset:1024
	v_pk_mul_f32 v[12:13], v[22:23], v[34:35] op_sel_hi:[1,0]
	v_pk_mul_f32 v[14:15], v[20:21], v[34:35] op_sel_hi:[1,0]
	v_pk_add_f32 v[6:7], v[148:149], 1.0 op_sel_hi:[1,0]
	v_pk_mul_f32 v[0:1], v[142:143], v[14:15]
	v_pk_mul_f32 v[2:3], v[144:145], v[12:13]
	v_pk_add_f32 v[4:5], v[146:147], 1.0 op_sel_hi:[1,0]
	v_pk_fma_f32 v[2:3], v[6:7], v[2:3], v[152:153]
	v_pk_fma_f32 v[0:1], v[4:5], v[0:1], v[150:151]
	s_nop 0
	v_cvt_pk_bf16_f32 v0, v0, v1
	v_cvt_pk_bf16_f32 v1, v2, v3
	global_store_dwordx2 v[32:33], v[0:1], off offset:1536

.LBB0_153:
	v_ashrrev_i32_e32 v32, 12, v32
	v_add_u32_e32 v32, 1, v32
	v_cndmask_b32_e64 v90, v32, 0, s[10:11]
	s_mov_b64 s[10:11], -1
	s_and_b64 vcc, exec, s[24:25]
	v_ashrrev_i32_e32 v91, 31, v90
	s_cbranch_vccz .LBB0_155
	v_lshl_add_u64 v[32:33], v[52:53], 0, v[90:91]
	v_mov_b64_e32 v[34:35], s[2:3]
	v_mad_u64_u32 v[34:35], s[10:11], v32, s73, v[34:35]
	v_mad_i32_i24 v35, v33, s73, v35
	v_lshl_add_u64 v[40:41], v[34:35], 0, v[192:193]
	v_add_co_u32_e32 v36, vcc, s70, v40
	global_load_dwordx4 v[32:35], v[54:55], off
	s_nop 0
	v_addc_co_u32_e32 v37, vcc, 0, v41, vcc
	global_load_dwordx4 v[36:39], v[36:37], off
	v_lshl_add_u64 v[116:117], v[40:41], 0, s[82:83]
	global_load_dwordx4 v[118:121], v[54:55], off offset:1024
	global_load_dwordx4 v[122:125], v[116:117], off offset:1024
	global_load_dwordx4 v[126:129], v[54:55], off offset:2048
	global_load_dwordx4 v[130:133], v[116:117], off offset:2048
	global_load_dwordx4 v[134:137], v[54:55], off offset:3072
	global_load_dwordx4 v[138:141], v[116:117], off offset:3072
	s_waitcnt vmcnt(0)
	v_and_b32_e32 v99, 0xffff0000, v82
	v_and_b32_e32 v98, 0xffff0000, v80
	v_lshlrev_b32_e32 v43, 16, v82
	v_lshlrev_b32_e32 v42, 16, v80
	v_pk_mul_f32 v[44:45], v[98:99], v[98:99]
	v_and_b32_e32 v107, 0xffff0000, v78
	v_and_b32_e32 v106, 0xffff0000, v76
	v_lshlrev_b32_e32 v101, 16, v83
	v_lshlrev_b32_e32 v100, 16, v81
	v_pk_fma_f32 v[44:45], v[42:43], v[42:43], v[44:45]
	v_lshlrev_b32_e32 v105, 16, v78
	v_lshlrev_b32_e32 v104, 16, v76
	v_pk_mul_f32 v[46:47], v[106:107], v[106:107]
	v_and_b32_e32 v103, 0xffff0000, v83
	v_and_b32_e32 v102, 0xffff0000, v81
	v_pk_fma_f32 v[44:45], v[100:101], v[100:101], v[44:45]
	v_lshlrev_b32_e32 v109, 16, v79
	v_lshlrev_b32_e32 v108, 16, v77
	v_pk_fma_f32 v[46:47], v[104:105], v[104:105], v[46:47]
	v_pk_fma_f32 v[44:45], v[102:103], v[102:103], v[44:45]
	v_and_b32_e32 v111, 0xffff0000, v79
	v_and_b32_e32 v110, 0xffff0000, v77
	v_pk_fma_f32 v[46:47], v[108:109], v[108:109], v[46:47]
	v_add_f32_e32 v44, v44, v45
	v_pk_fma_f32 v[46:47], v[110:111], v[110:111], v[46:47]
	s_mov_b32 s10, 0x800000
	v_add_f32_e32 v44, v47, v44
	v_add_f32_e32 v44, v46, v44
	ds_bpermute_b32 v45, v49, v44
	s_waitcnt lgkmcnt(0)
	v_add_f32_e32 v44, v44, v45
	ds_bpermute_b32 v45, v92, v44
	s_waitcnt lgkmcnt(0)
	v_add_f32_e32 v44, v44, v45
	ds_bpermute_b32 v45, v93, v44
	s_waitcnt lgkmcnt(0)
	v_add_f32_e32 v44, v44, v45
	ds_bpermute_b32 v45, v94, v44
	s_waitcnt lgkmcnt(0)
	v_add_f32_e32 v44, v44, v45
	ds_bpermute_b32 v45, v95, v44
	s_waitcnt lgkmcnt(0)
	v_add_f32_e32 v46, v44, v45
	ds_bpermute_b32 v47, v96, v46
	v_lshlrev_b64 v[44:45], 12, v[86:87]
	v_lshl_add_u64 v[112:113], v[56:57], 0, v[44:45]
	v_mov_b32_e32 v44, v101
	v_mov_b32_e32 v101, v102
	s_waitcnt lgkmcnt(0)
	v_add_f32_e32 v45, v46, v47
	v_fmamk_f32 v45, v45, 0x3a800000, v207
	v_mul_f32_e32 v46, 0x4b800000, v45
	v_cmp_gt_f32_e32 vcc, s10, v45
	v_mov_b32_e32 v47, v99
	v_mov_b32_e32 v99, v107
	v_cndmask_b32_e32 v45, v45, v46, vcc
	v_rsq_f32_e32 v63, v45
	v_mov_b32_e32 v46, v43
	v_mov_b32_e32 v45, v103
	s_mov_b64 s[10:11], 0
	v_mul_f32_e32 v43, 0x45800000, v63
	v_cndmask_b32_e32 v114, v63, v43, vcc
	v_pk_mul_f32 v[44:45], v[44:45], v[114:115] op_sel_hi:[1,0]
	v_pk_mul_f32 v[46:47], v[46:47], v[114:115] op_sel_hi:[1,0]
	v_pk_mul_f32 v[34:35], v[34:35], v[44:45]
	v_pk_mul_f32 v[32:33], v[32:33], v[46:47]
	v_pk_fma_f32 v[46:47], v[38:39], v[34:35], v[18:19]
	v_pk_fma_f32 v[44:45], v[36:37], v[32:33], v[16:17]
	global_store_dwordx4 v[112:113], v[44:47], off
	s_nop 1
	v_mov_b32_e32 v43, v98
	v_pk_mul_f32 v[40:41], v[42:43], v[114:115] op_sel_hi:[1,0]
	v_pk_mul_f32 v[42:43], v[100:101], v[114:115] op_sel_hi:[1,0]
	v_mov_b32_e32 v98, v105
	v_mov_b32_e32 v100, v109
	v_mov_b32_e32 v101, v111
	v_pk_mul_f32 v[98:99], v[98:99], v[114:115] op_sel_hi:[1,0]
	v_pk_mul_f32 v[100:101], v[100:101], v[114:115] op_sel_hi:[1,0]
	v_mov_b32_e32 v105, v106
	v_mov_b32_e32 v109, v110
	v_pk_mul_f32 v[102:103], v[104:105], v[114:115] op_sel_hi:[1,0]
	v_pk_mul_f32 v[104:105], v[108:109], v[114:115] op_sel_hi:[1,0]
	v_pk_mul_f32 v[34:35], v[120:121], v[42:43]
	v_pk_mul_f32 v[32:33], v[118:119], v[40:41]
	v_pk_fma_f32 v[42:43], v[124:125], v[34:35], v[22:23]
	v_pk_fma_f32 v[40:41], v[122:123], v[32:33], v[20:21]
	global_store_dwordx4 v[112:113], v[40:43], off offset:1024
	s_nop 1
	v_pk_mul_f32 v[34:35], v[128:129], v[100:101]
	v_pk_mul_f32 v[32:33], v[126:127], v[98:99]
	v_pk_fma_f32 v[34:35], v[132:133], v[34:35], v[26:27]
	v_pk_fma_f32 v[32:33], v[130:131], v[32:33], v[24:25]
	global_store_dwordx4 v[112:113], v[32:35], off offset:2048
	s_nop 1
	v_pk_mul_f32 v[38:39], v[136:137], v[104:105]
	v_pk_mul_f32 v[36:37], v[134:135], v[102:103]
	v_pk_fma_f32 v[38:39], v[140:141], v[38:39], v[30:31]
	v_pk_fma_f32 v[36:37], v[138:139], v[36:37], v[28:29]
	global_store_dwordx4 v[112:113], v[36:39], off offset:3072
	s_nop 1

.LBB0_157:
	s_waitcnt vmcnt(0)
	v_lshl_add_u64 v[16:17], s[18:19], 0, v[90:91]
	v_mov_b64_e32 v[18:19], s[2:3]
	v_mad_u64_u32 v[24:25], s[10:11], v16, s73, v[18:19]
	v_mov_b32_e32 v16, v25
	v_mad_u64_u32 v[16:17], s[10:11], v17, s73, v[16:17]
	v_mov_b32_e32 v25, v16
	s_mov_b64 s[10:11], 0x1000
	v_lshl_add_u64 v[28:29], v[24:25], 0, s[10:11]
	v_lshl_add_u64 v[20:21], v[28:29], 0, v[192:193]
	global_load_dwordx4 v[16:19], v[58:59], off
	v_lshl_add_u64 v[30:31], v[24:25], 0, v[192:193]
	global_load_dwordx4 v[20:23], v[20:21], off
	v_mov_b32_e32 v98, v41
	global_load_dwordx4 v[24:27], v[30:31], off
	v_lshl_add_u64 v[154:155], v[28:29], 0, v[192:193]
	global_load_dwordx4 v[118:121], v[58:59], off offset:1024
	global_load_dwordx4 v[122:125], v[154:155], off offset:1024
	global_load_dwordx4 v[126:129], v[30:31], off offset:1024
	global_load_dwordx4 v[130:133], v[58:59], off offset:2048
	global_load_dwordx4 v[134:137], v[154:155], off offset:2048
	global_load_dwordx4 v[138:141], v[30:31], off offset:2048
	global_load_dwordx4 v[142:145], v[58:59], off offset:3072
	global_load_dwordx4 v[146:149], v[154:155], off offset:3072
	global_load_dwordx4 v[150:153], v[30:31], off offset:3072
	v_mov_b32_e32 v99, v45
	v_mov_b32_e32 v90, v40
	v_mov_b32_e32 v91, v44
	v_pk_mul_f32 v[98:99], v[98:99], v[98:99]
	v_mov_b32_e32 v100, v37
	v_pk_fma_f32 v[90:91], v[90:91], v[90:91], v[98:99]
	v_mov_b32_e32 v98, v42
	v_mov_b32_e32 v99, v46
	v_pk_fma_f32 v[90:91], v[98:99], v[98:99], v[90:91]
	v_mov_b32_e32 v98, v43
	v_mov_b32_e32 v99, v47
	v_mov_b32_e32 v101, v33
	v_pk_fma_f32 v[90:91], v[98:99], v[98:99], v[90:91]
	v_mov_b32_e32 v98, v36
	v_mov_b32_e32 v99, v32
	v_pk_mul_f32 v[100:101], v[100:101], v[100:101]
	v_add_f32_e32 v63, v90, v91
	v_pk_fma_f32 v[98:99], v[98:99], v[98:99], v[100:101]
	v_mov_b32_e32 v100, v38
	v_mov_b32_e32 v101, v34
	v_pk_fma_f32 v[98:99], v[100:101], v[100:101], v[98:99]
	v_mov_b32_e32 v100, v39
	v_mov_b32_e32 v101, v35
	v_pk_fma_f32 v[98:99], v[100:101], v[100:101], v[98:99]
	s_mov_b32 s10, 0x800000
	v_add_f32_e32 v63, v99, v63
	v_add_f32_e32 v63, v98, v63
	ds_bpermute_b32 v65, v49, v63
	v_lshlrev_b64 v[86:87], 11, v[86:87]
	v_lshl_add_u64 v[86:87], v[60:61], 0, v[86:87]
	s_waitcnt lgkmcnt(0)
	v_add_f32_e32 v63, v63, v65
	ds_bpermute_b32 v65, v92, v63
	s_waitcnt lgkmcnt(0)
	v_add_f32_e32 v63, v63, v65
	ds_bpermute_b32 v65, v93, v63
	s_waitcnt lgkmcnt(0)
	v_add_f32_e32 v63, v63, v65
	ds_bpermute_b32 v65, v94, v63
	s_waitcnt lgkmcnt(0)
	v_add_f32_e32 v63, v63, v65
	ds_bpermute_b32 v65, v95, v63
	s_waitcnt lgkmcnt(0)
	v_add_f32_e32 v63, v63, v65
	ds_bpermute_b32 v65, v96, v63
	s_waitcnt lgkmcnt(0)
	v_add_f32_e32 v63, v63, v65
	v_fmamk_f32 v63, v63, 0x3a800000, v207
	v_mul_f32_e32 v65, 0x4b800000, v63
	v_cmp_gt_f32_e32 vcc, s10, v63
	s_waitcnt vmcnt(0)
	v_pk_add_f32 v[22:23], v[22:23], 1.0 op_sel_hi:[1,0]
	v_cndmask_b32_e32 v63, v63, v65, vcc
	v_rsq_f32_e32 v65, v63
	v_pk_add_f32 v[20:21], v[20:21], 1.0 op_sel_hi:[1,0]
	v_mov_b32_e32 v63, v193
	v_mul_f32_e32 v67, 0x45800000, v65
	v_cndmask_b32_e32 v90, v65, v67, vcc
	v_pk_mul_f32 v[46:47], v[46:47], v[90:91] op_sel_hi:[1,0]
	v_pk_mul_f32 v[44:45], v[44:45], v[90:91] op_sel_hi:[1,0]
	v_pk_mul_f32 v[18:19], v[18:19], v[46:47]
	v_pk_mul_f32 v[16:17], v[16:17], v[44:45]
	v_pk_fma_f32 v[18:19], v[22:23], v[18:19], v[26:27]
	v_pk_fma_f32 v[16:17], v[20:21], v[16:17], v[24:25]
	v_cvt_pk_bf16_f32 v16, v16, v17
	v_cvt_pk_bf16_f32 v17, v18, v19
	global_store_dwordx2 v[86:87], v[16:17], off
	v_pk_mul_f32 v[42:43], v[42:43], v[90:91] op_sel_hi:[1,0]
	v_pk_mul_f32 v[40:41], v[40:41], v[90:91] op_sel_hi:[1,0]
	v_mov_b32_e32 v65, v193
	v_pk_mul_f32 v[34:35], v[34:35], v[90:91] op_sel_hi:[1,0]
	v_pk_mul_f32 v[32:33], v[32:33], v[90:91] op_sel_hi:[1,0]
	v_mov_b32_e32 v67, v193
	v_pk_add_f32 v[22:23], v[124:125], 1.0 op_sel_hi:[1,0]
	v_pk_mul_f32 v[16:17], v[118:119], v[40:41]
	v_pk_mul_f32 v[18:19], v[120:121], v[42:43]
	v_pk_add_f32 v[20:21], v[122:123], 1.0 op_sel_hi:[1,0]
	v_pk_fma_f32 v[18:19], v[22:23], v[18:19], v[128:129]
	v_pk_fma_f32 v[16:17], v[20:21], v[16:17], v[126:127]
	v_cvt_pk_bf16_f32 v16, v16, v17
	v_cvt_pk_bf16_f32 v17, v18, v19
	global_store_dwordx2 v[86:87], v[16:17], off offset:512
	v_pk_add_f32 v[22:23], v[136:137], 1.0 op_sel_hi:[1,0]
	v_pk_mul_f32 v[16:17], v[130:131], v[32:33]
	v_pk_mul_f32 v[18:19], v[132:133], v[34:35]
	v_pk_add_f32 v[20:21], v[134:135], 1.0 op_sel_hi:[1,0]
	v_pk_fma_f32 v[18:19], v[22:23], v[18:19], v[140:141]
	v_pk_fma_f32 v[16:17], v[20:21], v[16:17], v[138:139]
	v_cvt_pk_bf16_f32 v16, v16, v17
	v_cvt_pk_bf16_f32 v17, v18, v19
	global_store_dwordx2 v[86:87], v[16:17], off offset:1024
	v_pk_mul_f32 v[28:29], v[38:39], v[90:91] op_sel_hi:[1,0]
	v_pk_mul_f32 v[30:31], v[36:37], v[90:91] op_sel_hi:[1,0]
	v_pk_add_f32 v[22:23], v[148:149], 1.0 op_sel_hi:[1,0]
	v_pk_mul_f32 v[16:17], v[142:143], v[30:31]
	v_pk_mul_f32 v[18:19], v[144:145], v[28:29]
	v_pk_add_f32 v[20:21], v[146:147], 1.0 op_sel_hi:[1,0]
	v_pk_fma_f32 v[18:19], v[22:23], v[18:19], v[152:153]
	v_pk_fma_f32 v[16:17], v[20:21], v[16:17], v[150:151]
	s_nop 0
	v_cvt_pk_bf16_f32 v16, v16, v17
	v_cvt_pk_bf16_f32 v17, v18, v19
	global_store_dwordx2 v[86:87], v[16:17], off offset:1536
	s_and_saveexec_b64 s[10:11], s[8:9]
	s_cbranch_execz .LBB0_132
	v_ashrrev_i32_e32 v16, 12, v88
	v_add_u32_e32 v16, 1, v16
	v_cndmask_b32_e64 v32, v16, 0, s[6:7]
	s_mov_b64 s[6:7], -1
	s_and_b64 vcc, exec, s[24:25]
	v_ashrrev_i32_e32 v33, 31, v32
	v_ashrrev_i32_e32 v85, 31, v84
	s_cbranch_vccz .LBB0_160
	v_lshl_add_u64 v[16:17], v[52:53], 0, v[32:33]
	v_mov_b64_e32 v[18:19], s[2:3]
	v_mad_u64_u32 v[18:19], s[6:7], v16, s73, v[18:19]
	v_mad_i32_i24 v19, v17, s73, v19
	v_lshl_add_u64 v[24:25], v[18:19], 0, v[192:193]
	v_add_co_u32_e32 v20, vcc, s70, v24
	global_load_dwordx4 v[16:19], v[54:55], off
	s_nop 0
	v_addc_co_u32_e32 v21, vcc, 0, v25, vcc
	global_load_dwordx4 v[20:23], v[20:21], off
	v_lshl_add_u64 v[90:91], v[24:25], 0, s[82:83]
	global_load_dwordx4 v[118:121], v[54:55], off offset:1024
	global_load_dwordx4 v[122:125], v[90:91], off offset:1024
	global_load_dwordx4 v[126:129], v[54:55], off offset:2048
	global_load_dwordx4 v[130:133], v[90:91], off offset:2048
	global_load_dwordx4 v[134:137], v[54:55], off offset:3072
	global_load_dwordx4 v[138:141], v[90:91], off offset:3072
	v_and_b32_e32 v35, 0xffff0000, v74
	v_and_b32_e32 v34, 0xffff0000, v72
	v_lshlrev_b32_e32 v27, 16, v74
	v_lshlrev_b32_e32 v26, 16, v72
	v_pk_mul_f32 v[28:29], v[34:35], v[34:35]
	v_and_b32_e32 v43, 0xffff0000, v70
	v_and_b32_e32 v42, 0xffff0000, v68
	v_lshlrev_b32_e32 v37, 16, v75
	v_lshlrev_b32_e32 v36, 16, v73
	v_pk_fma_f32 v[28:29], v[26:27], v[26:27], v[28:29]
	v_lshlrev_b32_e32 v41, 16, v70
	v_lshlrev_b32_e32 v40, 16, v68
	v_pk_mul_f32 v[30:31], v[42:43], v[42:43]
	v_and_b32_e32 v39, 0xffff0000, v75
	v_and_b32_e32 v38, 0xffff0000, v73
	v_pk_fma_f32 v[28:29], v[36:37], v[36:37], v[28:29]
	v_lshlrev_b32_e32 v45, 16, v71
	v_lshlrev_b32_e32 v44, 16, v69
	v_pk_fma_f32 v[30:31], v[40:41], v[40:41], v[30:31]
	v_pk_fma_f32 v[28:29], v[38:39], v[38:39], v[28:29]
	v_and_b32_e32 v47, 0xffff0000, v71
	v_and_b32_e32 v46, 0xffff0000, v69
	v_pk_fma_f32 v[30:31], v[44:45], v[44:45], v[30:31]
	v_add_f32_e32 v28, v28, v29
	v_pk_fma_f32 v[30:31], v[46:47], v[46:47], v[30:31]
	s_mov_b32 s6, 0x800000
	v_add_f32_e32 v28, v31, v28
	v_add_f32_e32 v28, v30, v28
	ds_bpermute_b32 v29, v49, v28
	s_waitcnt lgkmcnt(0)
	v_add_f32_e32 v28, v28, v29
	ds_bpermute_b32 v29, v92, v28
	s_waitcnt lgkmcnt(0)
	v_add_f32_e32 v28, v28, v29
	ds_bpermute_b32 v29, v93, v28
	s_waitcnt lgkmcnt(0)
	v_add_f32_e32 v28, v28, v29
	ds_bpermute_b32 v29, v94, v28
	s_waitcnt lgkmcnt(0)
	v_add_f32_e32 v28, v28, v29
	ds_bpermute_b32 v29, v95, v28
	s_waitcnt lgkmcnt(0)
	v_add_f32_e32 v30, v28, v29
	ds_bpermute_b32 v31, v96, v30
	v_lshlrev_b64 v[28:29], 12, v[84:85]
	v_lshl_add_u64 v[86:87], v[56:57], 0, v[28:29]
	v_mov_b32_e32 v28, v37
	s_waitcnt lgkmcnt(0)
	v_add_f32_e32 v29, v30, v31
	v_fmamk_f32 v29, v29, 0x3a800000, v207
	v_mul_f32_e32 v30, 0x4b800000, v29
	v_cmp_gt_f32_e32 vcc, s6, v29
	v_mov_b32_e32 v31, v35
	v_mov_b32_e32 v35, v43
	v_cndmask_b32_e32 v29, v29, v30, vcc
	v_rsq_f32_e32 v37, v29
	v_mov_b32_e32 v30, v27
	v_mov_b32_e32 v29, v39
	s_mov_b64 s[6:7], 0
	v_mul_f32_e32 v27, 0x45800000, v37
	v_cndmask_b32_e32 v88, v37, v27, vcc
	v_pk_mul_f32 v[28:29], v[28:29], v[88:89] op_sel_hi:[1,0]
	v_pk_mul_f32 v[30:31], v[30:31], v[88:89] op_sel_hi:[1,0]
	s_waitcnt vmcnt(0)
	v_pk_mul_f32 v[18:19], v[18:19], v[28:29]
	v_pk_mul_f32 v[16:17], v[16:17], v[30:31]
	v_pk_fma_f32 v[30:31], v[22:23], v[18:19], v[2:3]
	v_pk_fma_f32 v[28:29], v[20:21], v[16:17], v[0:1]
	global_store_dwordx4 v[86:87], v[28:31], off
	s_nop 1
	v_mov_b32_e32 v27, v34
	v_mov_b32_e32 v37, v38
	v_pk_mul_f32 v[24:25], v[26:27], v[88:89] op_sel_hi:[1,0]
	v_pk_mul_f32 v[26:27], v[36:37], v[88:89] op_sel_hi:[1,0]
	v_mov_b32_e32 v34, v41
	v_mov_b32_e32 v36, v45
	v_mov_b32_e32 v37, v47
	v_pk_mul_f32 v[34:35], v[34:35], v[88:89] op_sel_hi:[1,0]
	v_pk_mul_f32 v[36:37], v[36:37], v[88:89] op_sel_hi:[1,0]
	v_mov_b32_e32 v41, v42
	v_mov_b32_e32 v45, v46
	v_pk_mul_f32 v[38:39], v[40:41], v[88:89] op_sel_hi:[1,0]
	v_pk_mul_f32 v[40:41], v[44:45], v[88:89] op_sel_hi:[1,0]
	v_pk_mul_f32 v[18:19], v[120:121], v[26:27]
	v_pk_mul_f32 v[16:17], v[118:119], v[24:25]
	v_pk_fma_f32 v[26:27], v[124:125], v[18:19], v[6:7]
	v_pk_fma_f32 v[24:25], v[122:123], v[16:17], v[4:5]
	global_store_dwordx4 v[86:87], v[24:27], off offset:1024
	s_nop 1
	v_pk_mul_f32 v[18:19], v[128:129], v[36:37]
	v_pk_mul_f32 v[16:17], v[126:127], v[34:35]
	v_pk_fma_f32 v[18:19], v[132:133], v[18:19], v[10:11]
	v_pk_fma_f32 v[16:17], v[130:131], v[16:17], v[8:9]
	global_store_dwordx4 v[86:87], v[16:19], off offset:2048
	s_nop 1
	v_pk_mul_f32 v[22:23], v[136:137], v[40:41]
	v_pk_mul_f32 v[20:21], v[134:135], v[38:39]
	v_pk_fma_f32 v[22:23], v[140:141], v[22:23], v[14:15]
	v_pk_fma_f32 v[20:21], v[138:139], v[20:21], v[12:13]
	global_store_dwordx4 v[86:87], v[20:23], off offset:3072
	s_nop 1

.LBB0_221:
	s_add_u32 s42, s38, 0xfffc0080
	s_addc_u32 s43, s39, -1
	s_add_i32 s61, 0, 0x10000
	s_cmp_eq_u32 s59, 12
	s_cselect_b32 s45, s11, s43
	s_cselect_b32 s44, s13, s42
	s_cselect_b32 s43, s55, s58
	s_cselect_b32 s42, s56, s57
	s_add_i32 s64, 0, 0x14000
	v_add_u32_e32 v156, s61, v150
	v_add_u32_e32 v172, s64, v150
	ds_read_b128 v[140:143], v156
	ds_read_b128 v[144:147], v156 offset:1024
	ds_read_b128 v[152:155], v156 offset:2048
	ds_read_b128 v[156:159], v156 offset:3072
	ds_read_b128 v[160:163], v172
	ds_read_b128 v[164:167], v172 offset:1024
	ds_read_b128 v[168:171], v172 offset:2048
	ds_read_b128 v[172:175], v172 offset:3072
	v_lshl_add_u64 v[218:219], s[38:39], 0, v[138:139]
	s_add_i32 m0, s33, 0xc000
	ds_read_b128 v[176:179], v151
	ds_read_b128 v[180:183], v151 offset:1024
	ds_read_b128 v[184:187], v151 offset:2048
	ds_read_b128 v[188:191], v151 offset:3072
	ds_read_b128 v[194:197], v151 offset:4096
	ds_read_b128 v[198:201], v151 offset:5120
	ds_read_b128 v[202:205], v151 offset:6144
	ds_read_b128 v[214:217], v151 offset:7168
	global_load_lds_dwordx4 v[218:219], off
	v_lshl_add_u64 v[218:219], s[38:39], 0, v[136:137]
	s_add_i32 m0, s33, 0xe000
	s_nop 0
	global_load_lds_dwordx4 v[218:219], off
	s_waitcnt vmcnt(8)
	s_waitcnt lgkmcnt(0)
	s_barrier
	s_setprio 1
	v_mfma_f32_16x16x32_bf16 v[124:127], v[140:143], v[176:179], v[124:127]
	v_mfma_f32_16x16x32_bf16 v[120:123], v[152:155], v[176:179], v[120:123]
	v_mfma_f32_16x16x32_bf16 v[108:111], v[140:143], v[184:187], v[108:111]
	v_mfma_f32_16x16x32_bf16 v[104:107], v[152:155], v[184:187], v[104:107]
	v_mfma_f32_16x16x32_bf16 v[92:95], v[140:143], v[194:197], v[92:95]
	v_mfma_f32_16x16x32_bf16 v[88:91], v[152:155], v[194:197], v[88:91]
	v_mfma_f32_16x16x32_bf16 v[76:79], v[140:143], v[202:205], v[76:79]
	v_mfma_f32_16x16x32_bf16 v[72:75], v[152:155], v[202:205], v[72:75]
	v_mfma_f32_16x16x32_bf16 v[124:127], v[144:147], v[180:183], v[124:127]
	v_mfma_f32_16x16x32_bf16 v[120:123], v[156:159], v[180:183], v[120:123]
	v_mfma_f32_16x16x32_bf16 v[108:111], v[144:147], v[188:191], v[108:111]
	v_mfma_f32_16x16x32_bf16 v[104:107], v[156:159], v[188:191], v[104:107]
	v_mfma_f32_16x16x32_bf16 v[92:95], v[144:147], v[198:201], v[92:95]
	v_mfma_f32_16x16x32_bf16 v[88:91], v[156:159], v[198:201], v[88:91]
	v_mfma_f32_16x16x32_bf16 v[76:79], v[144:147], v[214:217], v[76:79]
	v_mfma_f32_16x16x32_bf16 v[72:75], v[156:159], v[214:217], v[72:75]
	v_mfma_f32_16x16x32_bf16 v[116:119], v[160:163], v[176:179], v[116:119]
	v_mfma_f32_16x16x32_bf16 v[112:115], v[168:171], v[176:179], v[112:115]
	v_mfma_f32_16x16x32_bf16 v[100:103], v[160:163], v[184:187], v[100:103]
	v_mfma_f32_16x16x32_bf16 v[96:99], v[168:171], v[184:187], v[96:99]
	v_mfma_f32_16x16x32_bf16 v[84:87], v[160:163], v[194:197], v[84:87]
	v_mfma_f32_16x16x32_bf16 v[80:83], v[168:171], v[194:197], v[80:83]
	v_mfma_f32_16x16x32_bf16 v[68:71], v[160:163], v[202:205], v[68:71]
	v_mfma_f32_16x16x32_bf16 v[64:67], v[168:171], v[202:205], v[64:67]
	v_mfma_f32_16x16x32_bf16 v[116:119], v[164:167], v[180:183], v[116:119]
	v_mfma_f32_16x16x32_bf16 v[112:115], v[172:175], v[180:183], v[112:115]
	v_mfma_f32_16x16x32_bf16 v[100:103], v[164:167], v[188:191], v[100:103]
	v_mfma_f32_16x16x32_bf16 v[96:99], v[172:175], v[188:191], v[96:99]
	v_mfma_f32_16x16x32_bf16 v[84:87], v[164:167], v[198:201], v[84:87]
	v_mfma_f32_16x16x32_bf16 v[80:83], v[172:175], v[198:201], v[80:83]
	v_mfma_f32_16x16x32_bf16 v[68:71], v[164:167], v[214:217], v[68:71]
	v_mfma_f32_16x16x32_bf16 v[64:67], v[172:175], v[214:217], v[64:67]
	s_setprio 0
	s_barrier
	s_add_i32 s61, s61, s27
	v_lshl_add_u64 v[218:219], s[42:43], 0, v[132:133]
	s_mov_b32 m0, s61
	ds_read_b128 v[176:179], v151 offset:16384
	ds_read_b128 v[180:183], v151 offset:17408
	ds_read_b128 v[184:187], v151 offset:18432
	ds_read_b128 v[188:191], v151 offset:19456
	ds_read_b128 v[194:197], v151 offset:20480
	ds_read_b128 v[198:201], v151 offset:21504
	ds_read_b128 v[202:205], v151 offset:22528
	ds_read_b128 v[214:217], v151 offset:23552
	global_load_lds_dwordx4 v[218:219], off
	s_add_i32 m0, s61, 0x2000
	s_add_u32 s62, s42, 0x40000
	v_lshl_add_u64 v[220:221], s[42:43], 0, v[128:129]
	s_addc_u32 s63, s43, 0
	s_add_i32 s61, s64, s27
	global_load_lds_dwordx4 v[220:221], off
	v_lshl_add_u64 v[222:223], s[62:63], 0, v[132:133]
	s_mov_b32 m0, s61
	v_lshl_add_u64 v[224:225], s[44:45], 0, v[130:131]
	global_load_lds_dwordx4 v[222:223], off
	v_lshl_add_u64 v[222:223], s[62:63], 0, v[128:129]
	s_add_i32 m0, s61, 0x2000
	s_nop 0
	global_load_lds_dwordx4 v[222:223], off
	v_lshl_add_u64 v[222:223], s[44:45], 0, v[134:135]
	s_mov_b32 m0, s33
	s_nop 0
	global_load_lds_dwordx4 v[222:223], off
	s_mov_b32 m0, s40
	s_nop 0
	global_load_lds_dwordx4 v[224:225], off
	s_waitcnt vmcnt(8)
	s_waitcnt lgkmcnt(0)
	s_barrier
	s_setprio 1
	v_mfma_f32_16x16x32_bf16 v[60:63], v[140:143], v[176:179], v[60:63]
	v_mfma_f32_16x16x32_bf16 v[56:59], v[152:155], v[176:179], v[56:59]
	v_mfma_f32_16x16x32_bf16 v[44:47], v[140:143], v[184:187], v[44:47]
	v_mfma_f32_16x16x32_bf16 v[40:43], v[152:155], v[184:187], v[40:43]
	v_mfma_f32_16x16x32_bf16 v[28:31], v[140:143], v[194:197], v[28:31]
	v_mfma_f32_16x16x32_bf16 v[24:27], v[152:155], v[194:197], v[24:27]
	v_mfma_f32_16x16x32_bf16 v[12:15], v[140:143], v[202:205], v[12:15]
	v_mfma_f32_16x16x32_bf16 v[8:11], v[152:155], v[202:205], v[8:11]
	v_mfma_f32_16x16x32_bf16 v[60:63], v[144:147], v[180:183], v[60:63]
	v_mfma_f32_16x16x32_bf16 v[56:59], v[156:159], v[180:183], v[56:59]
	v_mfma_f32_16x16x32_bf16 v[44:47], v[144:147], v[188:191], v[44:47]
	v_mfma_f32_16x16x32_bf16 v[40:43], v[156:159], v[188:191], v[40:43]
	v_mfma_f32_16x16x32_bf16 v[28:31], v[144:147], v[198:201], v[28:31]
	v_mfma_f32_16x16x32_bf16 v[24:27], v[156:159], v[198:201], v[24:27]
	v_mfma_f32_16x16x32_bf16 v[12:15], v[144:147], v[214:217], v[12:15]
	v_mfma_f32_16x16x32_bf16 v[8:11], v[156:159], v[214:217], v[8:11]
	v_mfma_f32_16x16x32_bf16 v[52:55], v[160:163], v[176:179], v[52:55]
	v_mfma_f32_16x16x32_bf16 v[48:51], v[168:171], v[176:179], v[48:51]
	v_mfma_f32_16x16x32_bf16 v[36:39], v[160:163], v[184:187], v[36:39]
	v_mfma_f32_16x16x32_bf16 v[32:35], v[168:171], v[184:187], v[32:35]
	v_mfma_f32_16x16x32_bf16 v[20:23], v[160:163], v[194:197], v[20:23]
	v_mfma_f32_16x16x32_bf16 v[16:19], v[168:171], v[194:197], v[16:19]
	v_mfma_f32_16x16x32_bf16 v[4:7], v[160:163], v[202:205], v[4:7]
	v_mfma_f32_16x16x32_bf16 v[0:3], v[168:171], v[202:205], v[0:3]
	v_mfma_f32_16x16x32_bf16 v[52:55], v[164:167], v[180:183], v[52:55]
	v_mfma_f32_16x16x32_bf16 v[48:51], v[172:175], v[180:183], v[48:51]
	v_mfma_f32_16x16x32_bf16 v[36:39], v[164:167], v[188:191], v[36:39]
	v_mfma_f32_16x16x32_bf16 v[32:35], v[172:175], v[188:191], v[32:35]
	v_mfma_f32_16x16x32_bf16 v[20:23], v[164:167], v[198:201], v[20:23]
	v_mfma_f32_16x16x32_bf16 v[16:19], v[172:175], v[198:201], v[16:19]
	v_mfma_f32_16x16x32_bf16 v[4:7], v[164:167], v[214:217], v[4:7]
	v_mfma_f32_16x16x32_bf16 v[0:3], v[172:175], v[214:217], v[0:3]
	s_setprio 0
	s_barrier
	s_add_i32 s61, 0, 0x18000
	s_add_i32 s62, 0, 0x1c000
	v_add_u32_e32 v156, s61, v150
	v_add_u32_e32 v172, s62, v150
	ds_read_b128 v[140:143], v156
	ds_read_b128 v[144:147], v156 offset:1024
	ds_read_b128 v[152:155], v156 offset:2048
	ds_read_b128 v[156:159], v156 offset:3072
	ds_read_b128 v[160:163], v172
	ds_read_b128 v[164:167], v172 offset:1024
	ds_read_b128 v[168:171], v172 offset:2048
	ds_read_b128 v[172:175], v172 offset:3072
	s_add_u32 s44, s44, 0x40000
	s_addc_u32 s45, s45, 0
	s_mov_b32 m0, s46
	v_lshl_add_u64 v[226:227], s[44:45], 0, v[134:135]
	ds_read_b128 v[176:179], v151 offset:32768
	ds_read_b128 v[180:183], v151 offset:33792
	ds_read_b128 v[184:187], v151 offset:34816
	ds_read_b128 v[188:191], v151 offset:35840
	ds_read_b128 v[194:197], v151 offset:36864
	ds_read_b128 v[198:201], v151 offset:37888
	ds_read_b128 v[202:205], v151 offset:38912
	ds_read_b128 v[214:217], v151 offset:39936
	global_load_lds_dwordx4 v[226:227], off
	v_lshl_add_u64 v[226:227], s[44:45], 0, v[130:131]
	s_mov_b32 m0, s47
	s_nop 0
	global_load_lds_dwordx4 v[226:227], off
	s_waitcnt vmcnt(8)
	s_waitcnt lgkmcnt(0)
	s_barrier
	s_setprio 1
	v_mfma_f32_16x16x32_bf16 v[124:127], v[140:143], v[176:179], v[124:127]
	v_mfma_f32_16x16x32_bf16 v[120:123], v[152:155], v[176:179], v[120:123]
	v_mfma_f32_16x16x32_bf16 v[108:111], v[140:143], v[184:187], v[108:111]
	v_mfma_f32_16x16x32_bf16 v[104:107], v[152:155], v[184:187], v[104:107]
	v_mfma_f32_16x16x32_bf16 v[92:95], v[140:143], v[194:197], v[92:95]
	v_mfma_f32_16x16x32_bf16 v[88:91], v[152:155], v[194:197], v[88:91]
	v_mfma_f32_16x16x32_bf16 v[76:79], v[140:143], v[202:205], v[76:79]
	v_mfma_f32_16x16x32_bf16 v[72:75], v[152:155], v[202:205], v[72:75]
	v_mfma_f32_16x16x32_bf16 v[124:127], v[144:147], v[180:183], v[124:127]
	v_mfma_f32_16x16x32_bf16 v[120:123], v[156:159], v[180:183], v[120:123]
	v_mfma_f32_16x16x32_bf16 v[108:111], v[144:147], v[188:191], v[108:111]
	v_mfma_f32_16x16x32_bf16 v[104:107], v[156:159], v[188:191], v[104:107]
	v_mfma_f32_16x16x32_bf16 v[92:95], v[144:147], v[198:201], v[92:95]
	v_mfma_f32_16x16x32_bf16 v[88:91], v[156:159], v[198:201], v[88:91]
	v_mfma_f32_16x16x32_bf16 v[76:79], v[144:147], v[214:217], v[76:79]
	v_mfma_f32_16x16x32_bf16 v[72:75], v[156:159], v[214:217], v[72:75]
	v_mfma_f32_16x16x32_bf16 v[116:119], v[160:163], v[176:179], v[116:119]
	v_mfma_f32_16x16x32_bf16 v[112:115], v[168:171], v[176:179], v[112:115]
	v_mfma_f32_16x16x32_bf16 v[100:103], v[160:163], v[184:187], v[100:103]
	v_mfma_f32_16x16x32_bf16 v[96:99], v[168:171], v[184:187], v[96:99]
	v_mfma_f32_16x16x32_bf16 v[84:87], v[160:163], v[194:197], v[84:87]
	v_mfma_f32_16x16x32_bf16 v[80:83], v[168:171], v[194:197], v[80:83]
	v_mfma_f32_16x16x32_bf16 v[68:71], v[160:163], v[202:205], v[68:71]
	v_mfma_f32_16x16x32_bf16 v[64:67], v[168:171], v[202:205], v[64:67]
	v_mfma_f32_16x16x32_bf16 v[116:119], v[164:167], v[180:183], v[116:119]
	v_mfma_f32_16x16x32_bf16 v[112:115], v[172:175], v[180:183], v[112:115]
	v_mfma_f32_16x16x32_bf16 v[100:103], v[164:167], v[188:191], v[100:103]
	v_mfma_f32_16x16x32_bf16 v[96:99], v[172:175], v[188:191], v[96:99]
	v_mfma_f32_16x16x32_bf16 v[84:87], v[164:167], v[198:201], v[84:87]
	v_mfma_f32_16x16x32_bf16 v[80:83], v[172:175], v[198:201], v[80:83]
	v_mfma_f32_16x16x32_bf16 v[68:71], v[164:167], v[214:217], v[68:71]
	v_mfma_f32_16x16x32_bf16 v[64:67], v[172:175], v[214:217], v[64:67]
	s_setprio 0
	s_barrier
	s_add_i32 s44, s61, s27
	v_lshl_add_u64 v[218:219], v[218:219], 0, s[76:77]
	s_mov_b32 m0, s44
	ds_read_b128 v[176:179], v151 offset:49152
	ds_read_b128 v[180:183], v151 offset:50176
	ds_read_b128 v[184:187], v151 offset:51200
	ds_read_b128 v[188:191], v151 offset:52224
	ds_read_b128 v[194:197], v151 offset:53248
	ds_read_b128 v[198:201], v151 offset:54272
	ds_read_b128 v[202:205], v151 offset:55296
	ds_read_b128 v[214:217], v151 offset:56320
	global_load_lds_dwordx4 v[218:219], off
	s_add_i32 m0, s44, 0x2000
	s_add_u32 s42, s42, 0x40080
	v_lshl_add_u64 v[218:219], v[220:221], 0, s[76:77]
	s_addc_u32 s43, s43, 0
	s_add_i32 s44, s62, s27
	global_load_lds_dwordx4 v[218:219], off
	v_lshl_add_u64 v[218:219], s[42:43], 0, v[132:133]
	s_mov_b32 m0, s44
	s_nop 0
	global_load_lds_dwordx4 v[218:219], off
	v_lshl_add_u64 v[218:219], s[42:43], 0, v[128:129]
	s_add_i32 m0, s44, 0x2000
	s_nop 0
	global_load_lds_dwordx4 v[218:219], off
	v_lshl_add_u64 v[218:219], v[222:223], 0, s[76:77]
	s_mov_b32 m0, s52
	s_nop 0
	global_load_lds_dwordx4 v[218:219], off
	v_lshl_add_u64 v[218:219], v[224:225], 0, s[76:77]
	s_mov_b32 m0, s53
	s_nop 0
	global_load_lds_dwordx4 v[218:219], off
	s_waitcnt vmcnt(8)
	s_waitcnt lgkmcnt(0)
	s_barrier
	s_setprio 1
	v_mfma_f32_16x16x32_bf16 v[60:63], v[140:143], v[176:179], v[60:63]
	v_mfma_f32_16x16x32_bf16 v[56:59], v[152:155], v[176:179], v[56:59]
	v_mfma_f32_16x16x32_bf16 v[44:47], v[140:143], v[184:187], v[44:47]
	v_mfma_f32_16x16x32_bf16 v[40:43], v[152:155], v[184:187], v[40:43]
	v_mfma_f32_16x16x32_bf16 v[28:31], v[140:143], v[194:197], v[28:31]
	v_mfma_f32_16x16x32_bf16 v[24:27], v[152:155], v[194:197], v[24:27]
	v_mfma_f32_16x16x32_bf16 v[12:15], v[140:143], v[202:205], v[12:15]
	v_mfma_f32_16x16x32_bf16 v[8:11], v[152:155], v[202:205], v[8:11]
	v_mfma_f32_16x16x32_bf16 v[60:63], v[144:147], v[180:183], v[60:63]
	v_mfma_f32_16x16x32_bf16 v[56:59], v[156:159], v[180:183], v[56:59]
	v_mfma_f32_16x16x32_bf16 v[44:47], v[144:147], v[188:191], v[44:47]
	v_mfma_f32_16x16x32_bf16 v[40:43], v[156:159], v[188:191], v[40:43]
	v_mfma_f32_16x16x32_bf16 v[28:31], v[144:147], v[198:201], v[28:31]
	v_mfma_f32_16x16x32_bf16 v[24:27], v[156:159], v[198:201], v[24:27]
	v_mfma_f32_16x16x32_bf16 v[12:15], v[144:147], v[214:217], v[12:15]
	v_mfma_f32_16x16x32_bf16 v[8:11], v[156:159], v[214:217], v[8:11]
	v_mfma_f32_16x16x32_bf16 v[52:55], v[160:163], v[176:179], v[52:55]
	v_mfma_f32_16x16x32_bf16 v[48:51], v[168:171], v[176:179], v[48:51]
	v_mfma_f32_16x16x32_bf16 v[36:39], v[160:163], v[184:187], v[36:39]
	v_mfma_f32_16x16x32_bf16 v[32:35], v[168:171], v[184:187], v[32:35]
	v_mfma_f32_16x16x32_bf16 v[20:23], v[160:163], v[194:197], v[20:23]
	v_mfma_f32_16x16x32_bf16 v[16:19], v[168:171], v[194:197], v[16:19]
	v_mfma_f32_16x16x32_bf16 v[4:7], v[160:163], v[202:205], v[4:7]
	v_mfma_f32_16x16x32_bf16 v[0:3], v[168:171], v[202:205], v[0:3]
	v_mfma_f32_16x16x32_bf16 v[52:55], v[164:167], v[180:183], v[52:55]
	v_mfma_f32_16x16x32_bf16 v[48:51], v[172:175], v[180:183], v[48:51]
	v_mfma_f32_16x16x32_bf16 v[36:39], v[164:167], v[188:191], v[36:39]
	v_mfma_f32_16x16x32_bf16 v[32:35], v[172:175], v[188:191], v[32:35]
	v_mfma_f32_16x16x32_bf16 v[20:23], v[164:167], v[198:201], v[20:23]
	v_mfma_f32_16x16x32_bf16 v[16:19], v[172:175], v[198:201], v[16:19]
	v_mfma_f32_16x16x32_bf16 v[4:7], v[164:167], v[214:217], v[4:7]
	v_mfma_f32_16x16x32_bf16 v[0:3], v[172:175], v[214:217], v[0:3]
	s_setprio 0
	s_barrier
	s_add_i32 s59, s59, 2
	s_add_u32 s57, s57, 0x100
	s_addc_u32 s58, s58, 0
	s_add_u32 s38, s38, 0x100
	s_addc_u32 s39, s39, 0
	s_cmp_gt_u32 s59, 13
	s_cbranch_scc0 .LBB0_221
	s_and_b64 vcc, exec, s[8:9]
	s_cbranch_vccz .LBB0_224
	s_barrier

.LBB0_278:
	s_add_u32 s11, s38, s9
	s_addc_u32 s13, s39, 0
	s_add_u32 s54, s11, 0x100
	s_addc_u32 s55, s13, 0
	s_and_b64 s[52:53], s[46:47], exec
	s_cselect_b32 s55, s15, s55
	s_cselect_b32 s54, s14, s54
	s_add_u32 s9, s42, s9
	s_addc_u32 s52, s43, 0
	s_add_u32 s9, s9, 0x100
	s_addc_u32 s52, s52, 0
	s_add_i32 s83, 0, 0x10000
	s_and_b64 s[46:47], s[46:47], exec
	s_cselect_b32 s57, s17, s52
	s_cselect_b32 s56, s16, s9
	s_add_i32 s47, 0, 0x14000
	s_add_u32 s72, s11, 0x10080
	s_addc_u32 s73, s13, 0
	s_add_i32 s82, s83, s26
	s_add_i32 m0, s27, 0xc000
	s_add_i32 s85, s27, 0xe000
	s_add_i32 s68, s82, 0x2000
	s_add_u32 s62, s56, 0x40000
	v_add_u32_e32 v150, s83, v136
	v_add_u32_e32 v166, s47, v136
	s_addc_u32 s63, s57, 0
	s_add_i32 s81, s47, s26
	ds_read_b128 v[138:141], v150
	ds_read_b128 v[142:145], v150 offset:1024
	ds_read_b128 v[146:149], v150 offset:2048
	ds_read_b128 v[150:153], v150 offset:3072
	ds_read_b128 v[154:157], v166
	ds_read_b128 v[158:161], v166 offset:1024
	ds_read_b128 v[162:165], v166 offset:2048
	ds_read_b128 v[166:169], v166 offset:3072
	s_add_i32 s80, s81, 0x2000
	s_add_i32 s67, 0, 0x18000
	s_add_i32 s13, 0, 0x1c000
	s_add_u32 s52, s54, 0x10000
	s_addc_u32 s53, s55, 0
	s_add_i32 s11, s67, s26
	s_add_i32 s9, s11, 0x2000
	s_add_u32 s46, s56, 0x40080
	s_addc_u32 s47, s57, 0
	s_add_i32 s84, s13, s26
	s_add_i32 s83, s84, 0x2000
	v_lshl_add_u64 v[190:191], s[72:73], 0, v[132:133]
	ds_read_b128 v[170:173], v137
	ds_read_b128 v[174:177], v137 offset:1024
	ds_read_b128 v[178:181], v137 offset:2048
	ds_read_b128 v[182:185], v137 offset:3072
	ds_read_b128 v[186:189], v137 offset:4096
	ds_read_b128 v[194:197], v137 offset:5120
	ds_read_b128 v[198:201], v137 offset:6144
	ds_read_b128 v[202:205], v137 offset:7168
	global_load_lds_dwordx4 v[190:191], off
	v_lshl_add_u64 v[190:191], s[72:73], 0, v[130:131]
	s_mov_b32 m0, s85
	s_nop 0
	global_load_lds_dwordx4 v[190:191], off
	s_waitcnt vmcnt(8)
	s_waitcnt lgkmcnt(0)
	s_barrier
	s_setprio 1
	v_mfma_f32_16x16x32_bf16 v[124:127], v[138:141], v[170:173], v[124:127]
	v_mfma_f32_16x16x32_bf16 v[120:123], v[146:149], v[170:173], v[120:123]
	v_mfma_f32_16x16x32_bf16 v[116:119], v[138:141], v[178:181], v[116:119]
	v_mfma_f32_16x16x32_bf16 v[112:115], v[146:149], v[178:181], v[112:115]
	v_mfma_f32_16x16x32_bf16 v[100:103], v[138:141], v[186:189], v[100:103]
	v_mfma_f32_16x16x32_bf16 v[96:99], v[146:149], v[186:189], v[96:99]
	v_mfma_f32_16x16x32_bf16 v[84:87], v[138:141], v[198:201], v[84:87]
	v_mfma_f32_16x16x32_bf16 v[80:83], v[146:149], v[198:201], v[80:83]
	v_mfma_f32_16x16x32_bf16 v[124:127], v[142:145], v[174:177], v[124:127]
	v_mfma_f32_16x16x32_bf16 v[120:123], v[150:153], v[174:177], v[120:123]
	v_mfma_f32_16x16x32_bf16 v[116:119], v[142:145], v[182:185], v[116:119]
	v_mfma_f32_16x16x32_bf16 v[112:115], v[150:153], v[182:185], v[112:115]
	v_mfma_f32_16x16x32_bf16 v[100:103], v[142:145], v[194:197], v[100:103]
	v_mfma_f32_16x16x32_bf16 v[96:99], v[150:153], v[194:197], v[96:99]
	v_mfma_f32_16x16x32_bf16 v[84:87], v[142:145], v[202:205], v[84:87]
	v_mfma_f32_16x16x32_bf16 v[80:83], v[150:153], v[202:205], v[80:83]
	v_mfma_f32_16x16x32_bf16 v[108:111], v[154:157], v[170:173], v[108:111]
	v_mfma_f32_16x16x32_bf16 v[104:107], v[162:165], v[170:173], v[104:107]
	v_mfma_f32_16x16x32_bf16 v[92:95], v[154:157], v[178:181], v[92:95]
	v_mfma_f32_16x16x32_bf16 v[88:91], v[162:165], v[178:181], v[88:91]
	v_mfma_f32_16x16x32_bf16 v[76:79], v[154:157], v[186:189], v[76:79]
	v_mfma_f32_16x16x32_bf16 v[72:75], v[162:165], v[186:189], v[72:75]
	v_mfma_f32_16x16x32_bf16 v[68:71], v[154:157], v[198:201], v[68:71]
	v_mfma_f32_16x16x32_bf16 v[64:67], v[162:165], v[198:201], v[64:67]
	v_mfma_f32_16x16x32_bf16 v[108:111], v[158:161], v[174:177], v[108:111]
	v_mfma_f32_16x16x32_bf16 v[104:107], v[166:169], v[174:177], v[104:107]
	v_mfma_f32_16x16x32_bf16 v[92:95], v[158:161], v[182:185], v[92:95]
	v_mfma_f32_16x16x32_bf16 v[88:91], v[166:169], v[182:185], v[88:91]
	v_mfma_f32_16x16x32_bf16 v[76:79], v[158:161], v[194:197], v[76:79]
	v_mfma_f32_16x16x32_bf16 v[72:75], v[166:169], v[194:197], v[72:75]
	v_mfma_f32_16x16x32_bf16 v[68:71], v[158:161], v[202:205], v[68:71]
	v_mfma_f32_16x16x32_bf16 v[64:67], v[166:169], v[202:205], v[64:67]
	s_setprio 0
	s_barrier
	s_mov_b32 m0, s82
	v_lshl_add_u64 v[190:191], s[56:57], 0, v[192:193]
	ds_read_b128 v[170:173], v137 offset:16384
	ds_read_b128 v[174:177], v137 offset:17408
	ds_read_b128 v[178:181], v137 offset:18432
	ds_read_b128 v[182:185], v137 offset:19456
	ds_read_b128 v[186:189], v137 offset:20480
	ds_read_b128 v[194:197], v137 offset:21504
	ds_read_b128 v[198:201], v137 offset:22528
	ds_read_b128 v[202:205], v137 offset:23552
	global_load_lds_dwordx4 v[190:191], off
	v_lshl_add_u64 v[214:215], s[56:57], 0, v[128:129]
	s_mov_b32 m0, s68
	v_lshl_add_u64 v[216:217], s[62:63], 0, v[192:193]
	global_load_lds_dwordx4 v[214:215], off
	s_mov_b32 m0, s81
	v_lshl_add_u64 v[218:219], s[54:55], 0, v[130:131]
	global_load_lds_dwordx4 v[216:217], off
	v_lshl_add_u64 v[216:217], s[62:63], 0, v[128:129]
	s_mov_b32 m0, s80
	s_nop 0
	global_load_lds_dwordx4 v[216:217], off
	v_lshl_add_u64 v[216:217], s[54:55], 0, v[132:133]
	s_mov_b32 m0, s27
	s_nop 0
	global_load_lds_dwordx4 v[216:217], off
	s_mov_b32 m0, s33
	s_nop 0
	global_load_lds_dwordx4 v[218:219], off
	s_waitcnt vmcnt(8)
	s_waitcnt lgkmcnt(0)
	s_barrier
	s_setprio 1
	v_mfma_f32_16x16x32_bf16 v[60:63], v[138:141], v[170:173], v[60:63]
	v_mfma_f32_16x16x32_bf16 v[56:59], v[146:149], v[170:173], v[56:59]
	v_mfma_f32_16x16x32_bf16 v[52:55], v[138:141], v[178:181], v[52:55]
	v_mfma_f32_16x16x32_bf16 v[48:51], v[146:149], v[178:181], v[48:51]
	v_mfma_f32_16x16x32_bf16 v[36:39], v[138:141], v[186:189], v[36:39]
	v_mfma_f32_16x16x32_bf16 v[32:35], v[146:149], v[186:189], v[32:35]
	v_mfma_f32_16x16x32_bf16 v[20:23], v[138:141], v[198:201], v[20:23]
	v_mfma_f32_16x16x32_bf16 v[16:19], v[146:149], v[198:201], v[16:19]
	v_mfma_f32_16x16x32_bf16 v[60:63], v[142:145], v[174:177], v[60:63]
	v_mfma_f32_16x16x32_bf16 v[56:59], v[150:153], v[174:177], v[56:59]
	v_mfma_f32_16x16x32_bf16 v[52:55], v[142:145], v[182:185], v[52:55]
	v_mfma_f32_16x16x32_bf16 v[48:51], v[150:153], v[182:185], v[48:51]
	v_mfma_f32_16x16x32_bf16 v[36:39], v[142:145], v[194:197], v[36:39]
	v_mfma_f32_16x16x32_bf16 v[32:35], v[150:153], v[194:197], v[32:35]
	v_mfma_f32_16x16x32_bf16 v[20:23], v[142:145], v[202:205], v[20:23]
	v_mfma_f32_16x16x32_bf16 v[16:19], v[150:153], v[202:205], v[16:19]
	v_mfma_f32_16x16x32_bf16 v[44:47], v[154:157], v[170:173], v[44:47]
	v_mfma_f32_16x16x32_bf16 v[40:43], v[162:165], v[170:173], v[40:43]
	v_mfma_f32_16x16x32_bf16 v[28:31], v[154:157], v[178:181], v[28:31]
	v_mfma_f32_16x16x32_bf16 v[24:27], v[162:165], v[178:181], v[24:27]
	v_mfma_f32_16x16x32_bf16 v[12:15], v[154:157], v[186:189], v[12:15]
	v_mfma_f32_16x16x32_bf16 v[8:11], v[162:165], v[186:189], v[8:11]
	v_mfma_f32_16x16x32_bf16 v[4:7], v[154:157], v[198:201], v[4:7]
	v_mfma_f32_16x16x32_bf16 v[0:3], v[162:165], v[198:201], v[0:3]
	v_mfma_f32_16x16x32_bf16 v[44:47], v[158:161], v[174:177], v[44:47]
	v_mfma_f32_16x16x32_bf16 v[40:43], v[166:169], v[174:177], v[40:43]
	v_mfma_f32_16x16x32_bf16 v[28:31], v[158:161], v[182:185], v[28:31]
	v_mfma_f32_16x16x32_bf16 v[24:27], v[166:169], v[182:185], v[24:27]
	v_mfma_f32_16x16x32_bf16 v[12:15], v[158:161], v[194:197], v[12:15]
	v_mfma_f32_16x16x32_bf16 v[8:11], v[166:169], v[194:197], v[8:11]
	v_mfma_f32_16x16x32_bf16 v[4:7], v[158:161], v[202:205], v[4:7]
	v_mfma_f32_16x16x32_bf16 v[0:3], v[166:169], v[202:205], v[0:3]
	s_setprio 0
	s_barrier
	v_add_u32_e32 v150, s67, v136
	v_add_u32_e32 v166, s13, v136
	ds_read_b128 v[138:141], v150
	ds_read_b128 v[142:145], v150 offset:1024
	ds_read_b128 v[146:149], v150 offset:2048
	ds_read_b128 v[150:153], v150 offset:3072
	ds_read_b128 v[154:157], v166
	ds_read_b128 v[158:161], v166 offset:1024
	ds_read_b128 v[162:165], v166 offset:2048
	ds_read_b128 v[166:169], v166 offset:3072
	s_mov_b32 m0, s48
	v_lshl_add_u64 v[220:221], s[52:53], 0, v[132:133]
	ds_read_b128 v[170:173], v137 offset:32768
	ds_read_b128 v[174:177], v137 offset:33792
	ds_read_b128 v[178:181], v137 offset:34816
	ds_read_b128 v[182:185], v137 offset:35840
	ds_read_b128 v[186:189], v137 offset:36864
	ds_read_b128 v[194:197], v137 offset:37888
	ds_read_b128 v[198:201], v137 offset:38912
	ds_read_b128 v[202:205], v137 offset:39936
	global_load_lds_dwordx4 v[220:221], off
	v_lshl_add_u64 v[220:221], s[52:53], 0, v[130:131]
	s_mov_b32 m0, s49
	s_nop 0
	global_load_lds_dwordx4 v[220:221], off
	s_waitcnt vmcnt(8)
	s_waitcnt lgkmcnt(0)
	s_barrier
	s_setprio 1
	v_mfma_f32_16x16x32_bf16 v[124:127], v[138:141], v[170:173], v[124:127]
	v_mfma_f32_16x16x32_bf16 v[120:123], v[146:149], v[170:173], v[120:123]
	v_mfma_f32_16x16x32_bf16 v[116:119], v[138:141], v[178:181], v[116:119]
	v_mfma_f32_16x16x32_bf16 v[112:115], v[146:149], v[178:181], v[112:115]
	v_mfma_f32_16x16x32_bf16 v[100:103], v[138:141], v[186:189], v[100:103]
	v_mfma_f32_16x16x32_bf16 v[96:99], v[146:149], v[186:189], v[96:99]
	v_mfma_f32_16x16x32_bf16 v[84:87], v[138:141], v[198:201], v[84:87]
	v_mfma_f32_16x16x32_bf16 v[80:83], v[146:149], v[198:201], v[80:83]
	v_mfma_f32_16x16x32_bf16 v[124:127], v[142:145], v[174:177], v[124:127]
	v_mfma_f32_16x16x32_bf16 v[120:123], v[150:153], v[174:177], v[120:123]
	v_mfma_f32_16x16x32_bf16 v[116:119], v[142:145], v[182:185], v[116:119]
	v_mfma_f32_16x16x32_bf16 v[112:115], v[150:153], v[182:185], v[112:115]
	v_mfma_f32_16x16x32_bf16 v[100:103], v[142:145], v[194:197], v[100:103]
	v_mfma_f32_16x16x32_bf16 v[96:99], v[150:153], v[194:197], v[96:99]
	v_mfma_f32_16x16x32_bf16 v[84:87], v[142:145], v[202:205], v[84:87]
	v_mfma_f32_16x16x32_bf16 v[80:83], v[150:153], v[202:205], v[80:83]
	v_mfma_f32_16x16x32_bf16 v[108:111], v[154:157], v[170:173], v[108:111]
	v_mfma_f32_16x16x32_bf16 v[104:107], v[162:165], v[170:173], v[104:107]
	v_mfma_f32_16x16x32_bf16 v[92:95], v[154:157], v[178:181], v[92:95]
	v_mfma_f32_16x16x32_bf16 v[88:91], v[162:165], v[178:181], v[88:91]
	v_mfma_f32_16x16x32_bf16 v[76:79], v[154:157], v[186:189], v[76:79]
	v_mfma_f32_16x16x32_bf16 v[72:75], v[162:165], v[186:189], v[72:75]
	v_mfma_f32_16x16x32_bf16 v[68:71], v[154:157], v[198:201], v[68:71]
	v_mfma_f32_16x16x32_bf16 v[64:67], v[162:165], v[198:201], v[64:67]
	v_mfma_f32_16x16x32_bf16 v[108:111], v[158:161], v[174:177], v[108:111]
	v_mfma_f32_16x16x32_bf16 v[104:107], v[166:169], v[174:177], v[104:107]
	v_mfma_f32_16x16x32_bf16 v[92:95], v[158:161], v[182:185], v[92:95]
	v_mfma_f32_16x16x32_bf16 v[88:91], v[166:169], v[182:185], v[88:91]
	v_mfma_f32_16x16x32_bf16 v[76:79], v[158:161], v[194:197], v[76:79]
	v_mfma_f32_16x16x32_bf16 v[72:75], v[166:169], v[194:197], v[72:75]
	v_mfma_f32_16x16x32_bf16 v[68:71], v[158:161], v[202:205], v[68:71]
	v_mfma_f32_16x16x32_bf16 v[64:67], v[166:169], v[202:205], v[64:67]
	s_setprio 0
	s_barrier
	s_mov_b32 m0, s11
	v_lshl_add_u64 v[190:191], v[190:191], 0, s[76:77]
	ds_read_b128 v[170:173], v137 offset:49152
	ds_read_b128 v[174:177], v137 offset:50176
	ds_read_b128 v[178:181], v137 offset:51200
	ds_read_b128 v[182:185], v137 offset:52224
	ds_read_b128 v[186:189], v137 offset:53248
	ds_read_b128 v[194:197], v137 offset:54272
	ds_read_b128 v[198:201], v137 offset:55296
	ds_read_b128 v[202:205], v137 offset:56320
	global_load_lds_dwordx4 v[190:191], off
	v_lshl_add_u64 v[190:191], v[214:215], 0, s[76:77]
	s_mov_b32 m0, s9
	s_nop 0
	global_load_lds_dwordx4 v[190:191], off
	v_lshl_add_u64 v[190:191], s[46:47], 0, v[192:193]
	s_mov_b32 m0, s84
	s_nop 0
	global_load_lds_dwordx4 v[190:191], off
	v_lshl_add_u64 v[190:191], s[46:47], 0, v[128:129]
	s_mov_b32 m0, s83
	s_nop 0
	global_load_lds_dwordx4 v[190:191], off
	v_lshl_add_u64 v[190:191], v[216:217], 0, s[76:77]
	s_mov_b32 m0, s59
	s_nop 0
	global_load_lds_dwordx4 v[190:191], off
	v_lshl_add_u64 v[190:191], v[218:219], 0, s[76:77]
	s_mov_b32 m0, s61
	s_nop 0
	global_load_lds_dwordx4 v[190:191], off
	s_waitcnt vmcnt(8)
	s_waitcnt lgkmcnt(0)
	s_barrier
	s_setprio 1
	v_mfma_f32_16x16x32_bf16 v[60:63], v[138:141], v[170:173], v[60:63]
	v_mfma_f32_16x16x32_bf16 v[56:59], v[146:149], v[170:173], v[56:59]
	v_mfma_f32_16x16x32_bf16 v[52:55], v[138:141], v[178:181], v[52:55]
	v_mfma_f32_16x16x32_bf16 v[48:51], v[146:149], v[178:181], v[48:51]
	v_mfma_f32_16x16x32_bf16 v[36:39], v[138:141], v[186:189], v[36:39]
	v_mfma_f32_16x16x32_bf16 v[32:35], v[146:149], v[186:189], v[32:35]
	v_mfma_f32_16x16x32_bf16 v[20:23], v[138:141], v[198:201], v[20:23]
	v_mfma_f32_16x16x32_bf16 v[16:19], v[146:149], v[198:201], v[16:19]
	v_mfma_f32_16x16x32_bf16 v[60:63], v[142:145], v[174:177], v[60:63]
	v_mfma_f32_16x16x32_bf16 v[56:59], v[150:153], v[174:177], v[56:59]
	v_mfma_f32_16x16x32_bf16 v[52:55], v[142:145], v[182:185], v[52:55]
	v_mfma_f32_16x16x32_bf16 v[48:51], v[150:153], v[182:185], v[48:51]
	v_mfma_f32_16x16x32_bf16 v[36:39], v[142:145], v[194:197], v[36:39]
	v_mfma_f32_16x16x32_bf16 v[32:35], v[150:153], v[194:197], v[32:35]
	v_mfma_f32_16x16x32_bf16 v[20:23], v[142:145], v[202:205], v[20:23]
	v_mfma_f32_16x16x32_bf16 v[16:19], v[150:153], v[202:205], v[16:19]
	v_mfma_f32_16x16x32_bf16 v[44:47], v[154:157], v[170:173], v[44:47]
	v_mfma_f32_16x16x32_bf16 v[40:43], v[162:165], v[170:173], v[40:43]
	v_mfma_f32_16x16x32_bf16 v[28:31], v[154:157], v[178:181], v[28:31]
	v_mfma_f32_16x16x32_bf16 v[24:27], v[162:165], v[178:181], v[24:27]
	v_mfma_f32_16x16x32_bf16 v[12:15], v[154:157], v[186:189], v[12:15]
	v_mfma_f32_16x16x32_bf16 v[8:11], v[162:165], v[186:189], v[8:11]
	v_mfma_f32_16x16x32_bf16 v[4:7], v[154:157], v[198:201], v[4:7]
	v_mfma_f32_16x16x32_bf16 v[0:3], v[162:165], v[198:201], v[0:3]
	v_mfma_f32_16x16x32_bf16 v[44:47], v[158:161], v[174:177], v[44:47]
	v_mfma_f32_16x16x32_bf16 v[40:43], v[166:169], v[174:177], v[40:43]
	v_mfma_f32_16x16x32_bf16 v[28:31], v[158:161], v[182:185], v[28:31]
	v_mfma_f32_16x16x32_bf16 v[24:27], v[166:169], v[182:185], v[24:27]
	v_mfma_f32_16x16x32_bf16 v[12:15], v[158:161], v[194:197], v[12:15]
	v_mfma_f32_16x16x32_bf16 v[8:11], v[166:169], v[194:197], v[8:11]
	v_mfma_f32_16x16x32_bf16 v[4:7], v[158:161], v[202:205], v[4:7]
	v_mfma_f32_16x16x32_bf16 v[0:3], v[166:169], v[202:205], v[0:3]
	s_setprio 0
	s_barrier
	s_movk_i32 s9, 0x100
	s_andn2_b64 vcc, exec, s[44:45]
	s_mov_b64 s[46:47], -1
	s_mov_b64 s[44:45], 0
	s_cbranch_vccz .LBB0_278
	s_and_b64 vcc, exec, s[2:3]
	s_cbranch_vccz .LBB0_281
	s_barrier

.LBB0_299:
	s_add_u32 s14, s12, 0xfffc0080
	s_addc_u32 s15, s13, -1
	s_add_i32 s40, 0, 0x10000
	s_cmp_eq_u32 s39, 12
	s_cselect_b32 s17, s9, s15
	s_cselect_b32 s16, s11, s14
	s_cselect_b32 s15, s30, s38
	s_cselect_b32 s14, s31, s33
	s_add_i32 s52, 0, 0x14000
	v_add_u32_e32 v140, s40, v178
	v_add_u32_e32 v168, s52, v178
	ds_read_b128 v[128:131], v140
	ds_read_b128 v[132:135], v140 offset:1024
	ds_read_b128 v[136:139], v140 offset:2048
	ds_read_b128 v[140:143], v140 offset:3072
	ds_read_b128 v[156:159], v168
	ds_read_b128 v[160:163], v168 offset:1024
	ds_read_b128 v[164:167], v168 offset:2048
	ds_read_b128 v[168:171], v168 offset:3072
	v_lshl_add_u64 v[218:219], s[12:13], 0, v[154:155]
	s_add_i32 m0, s48, 0xc000
	ds_read_b128 v[172:175], v179
	ds_read_b128 v[180:183], v179 offset:1024
	ds_read_b128 v[184:187], v179 offset:2048
	ds_read_b128 v[188:191], v179 offset:3072
	ds_read_b128 v[194:197], v179 offset:4096
	ds_read_b128 v[198:201], v179 offset:5120
	ds_read_b128 v[202:205], v179 offset:6144
	ds_read_b128 v[214:217], v179 offset:7168
	global_load_lds_dwordx4 v[218:219], off
	v_lshl_add_u64 v[218:219], s[12:13], 0, v[152:153]
	s_add_i32 m0, s48, 0xe000
	s_nop 0
	global_load_lds_dwordx4 v[218:219], off
	s_waitcnt vmcnt(8)
	s_waitcnt lgkmcnt(0)
	s_barrier
	s_setprio 1
	v_mfma_f32_16x16x32_bf16 v[124:127], v[128:131], v[172:175], v[124:127]
	v_mfma_f32_16x16x32_bf16 v[120:123], v[136:139], v[172:175], v[120:123]
	v_mfma_f32_16x16x32_bf16 v[108:111], v[128:131], v[184:187], v[108:111]
	v_mfma_f32_16x16x32_bf16 v[104:107], v[136:139], v[184:187], v[104:107]
	v_mfma_f32_16x16x32_bf16 v[92:95], v[128:131], v[194:197], v[92:95]
	v_mfma_f32_16x16x32_bf16 v[88:91], v[136:139], v[194:197], v[88:91]
	v_mfma_f32_16x16x32_bf16 v[76:79], v[128:131], v[202:205], v[76:79]
	v_mfma_f32_16x16x32_bf16 v[72:75], v[136:139], v[202:205], v[72:75]
	v_mfma_f32_16x16x32_bf16 v[124:127], v[132:135], v[180:183], v[124:127]
	v_mfma_f32_16x16x32_bf16 v[120:123], v[140:143], v[180:183], v[120:123]
	v_mfma_f32_16x16x32_bf16 v[108:111], v[132:135], v[188:191], v[108:111]
	v_mfma_f32_16x16x32_bf16 v[104:107], v[140:143], v[188:191], v[104:107]
	v_mfma_f32_16x16x32_bf16 v[92:95], v[132:135], v[198:201], v[92:95]
	v_mfma_f32_16x16x32_bf16 v[88:91], v[140:143], v[198:201], v[88:91]
	v_mfma_f32_16x16x32_bf16 v[76:79], v[132:135], v[214:217], v[76:79]
	v_mfma_f32_16x16x32_bf16 v[72:75], v[140:143], v[214:217], v[72:75]
	v_mfma_f32_16x16x32_bf16 v[116:119], v[156:159], v[172:175], v[116:119]
	v_mfma_f32_16x16x32_bf16 v[112:115], v[164:167], v[172:175], v[112:115]
	v_mfma_f32_16x16x32_bf16 v[100:103], v[156:159], v[184:187], v[100:103]
	v_mfma_f32_16x16x32_bf16 v[96:99], v[164:167], v[184:187], v[96:99]
	v_mfma_f32_16x16x32_bf16 v[84:87], v[156:159], v[194:197], v[84:87]
	v_mfma_f32_16x16x32_bf16 v[80:83], v[164:167], v[194:197], v[80:83]
	v_mfma_f32_16x16x32_bf16 v[68:71], v[156:159], v[202:205], v[68:71]
	v_mfma_f32_16x16x32_bf16 v[64:67], v[164:167], v[202:205], v[64:67]
	v_mfma_f32_16x16x32_bf16 v[116:119], v[160:163], v[180:183], v[116:119]
	v_mfma_f32_16x16x32_bf16 v[112:115], v[168:171], v[180:183], v[112:115]
	v_mfma_f32_16x16x32_bf16 v[100:103], v[160:163], v[188:191], v[100:103]
	v_mfma_f32_16x16x32_bf16 v[96:99], v[168:171], v[188:191], v[96:99]
	v_mfma_f32_16x16x32_bf16 v[84:87], v[160:163], v[198:201], v[84:87]
	v_mfma_f32_16x16x32_bf16 v[80:83], v[168:171], v[198:201], v[80:83]
	v_mfma_f32_16x16x32_bf16 v[68:71], v[160:163], v[214:217], v[68:71]
	v_mfma_f32_16x16x32_bf16 v[64:67], v[168:171], v[214:217], v[64:67]
	s_setprio 0
	s_barrier
	s_add_i32 s40, s40, s61
	v_lshl_add_u64 v[218:219], s[14:15], 0, v[148:149]
	s_mov_b32 m0, s40
	ds_read_b128 v[172:175], v179 offset:16384
	ds_read_b128 v[180:183], v179 offset:17408
	ds_read_b128 v[184:187], v179 offset:18432
	ds_read_b128 v[188:191], v179 offset:19456
	ds_read_b128 v[194:197], v179 offset:20480
	ds_read_b128 v[198:201], v179 offset:21504
	ds_read_b128 v[202:205], v179 offset:22528
	ds_read_b128 v[214:217], v179 offset:23552
	global_load_lds_dwordx4 v[218:219], off
	s_add_i32 m0, s40, 0x2000
	s_add_u32 s44, s14, 0x40000
	v_lshl_add_u64 v[220:221], s[14:15], 0, v[144:145]
	s_addc_u32 s45, s15, 0
	s_add_i32 s40, s52, s61
	global_load_lds_dwordx4 v[220:221], off
	v_lshl_add_u64 v[222:223], s[44:45], 0, v[148:149]
	s_mov_b32 m0, s40
	v_lshl_add_u64 v[224:225], s[16:17], 0, v[146:147]
	global_load_lds_dwordx4 v[222:223], off
	v_lshl_add_u64 v[222:223], s[44:45], 0, v[144:145]
	s_add_i32 m0, s40, 0x2000
	s_nop 0
	global_load_lds_dwordx4 v[222:223], off
	v_lshl_add_u64 v[222:223], s[16:17], 0, v[150:151]
	s_mov_b32 m0, s48
	s_nop 0
	global_load_lds_dwordx4 v[222:223], off
	s_mov_b32 m0, s49
	s_nop 0
	global_load_lds_dwordx4 v[224:225], off
	s_waitcnt vmcnt(8)
	s_waitcnt lgkmcnt(0)
	s_barrier
	s_setprio 1
	v_mfma_f32_16x16x32_bf16 v[60:63], v[128:131], v[172:175], v[60:63]
	v_mfma_f32_16x16x32_bf16 v[56:59], v[136:139], v[172:175], v[56:59]
	v_mfma_f32_16x16x32_bf16 v[44:47], v[128:131], v[184:187], v[44:47]
	v_mfma_f32_16x16x32_bf16 v[40:43], v[136:139], v[184:187], v[40:43]
	v_mfma_f32_16x16x32_bf16 v[28:31], v[128:131], v[194:197], v[28:31]
	v_mfma_f32_16x16x32_bf16 v[24:27], v[136:139], v[194:197], v[24:27]
	v_mfma_f32_16x16x32_bf16 v[12:15], v[128:131], v[202:205], v[12:15]
	v_mfma_f32_16x16x32_bf16 v[8:11], v[136:139], v[202:205], v[8:11]
	v_mfma_f32_16x16x32_bf16 v[60:63], v[132:135], v[180:183], v[60:63]
	v_mfma_f32_16x16x32_bf16 v[56:59], v[140:143], v[180:183], v[56:59]
	v_mfma_f32_16x16x32_bf16 v[44:47], v[132:135], v[188:191], v[44:47]
	v_mfma_f32_16x16x32_bf16 v[40:43], v[140:143], v[188:191], v[40:43]
	v_mfma_f32_16x16x32_bf16 v[28:31], v[132:135], v[198:201], v[28:31]
	v_mfma_f32_16x16x32_bf16 v[24:27], v[140:143], v[198:201], v[24:27]
	v_mfma_f32_16x16x32_bf16 v[12:15], v[132:135], v[214:217], v[12:15]
	v_mfma_f32_16x16x32_bf16 v[8:11], v[140:143], v[214:217], v[8:11]
	v_mfma_f32_16x16x32_bf16 v[52:55], v[156:159], v[172:175], v[52:55]
	v_mfma_f32_16x16x32_bf16 v[48:51], v[164:167], v[172:175], v[48:51]
	v_mfma_f32_16x16x32_bf16 v[36:39], v[156:159], v[184:187], v[36:39]
	v_mfma_f32_16x16x32_bf16 v[32:35], v[164:167], v[184:187], v[32:35]
	v_mfma_f32_16x16x32_bf16 v[20:23], v[156:159], v[194:197], v[20:23]
	v_mfma_f32_16x16x32_bf16 v[16:19], v[164:167], v[194:197], v[16:19]
	v_mfma_f32_16x16x32_bf16 v[4:7], v[156:159], v[202:205], v[4:7]
	v_mfma_f32_16x16x32_bf16 v[0:3], v[164:167], v[202:205], v[0:3]
	v_mfma_f32_16x16x32_bf16 v[52:55], v[160:163], v[180:183], v[52:55]
	v_mfma_f32_16x16x32_bf16 v[48:51], v[168:171], v[180:183], v[48:51]
	v_mfma_f32_16x16x32_bf16 v[36:39], v[160:163], v[188:191], v[36:39]
	v_mfma_f32_16x16x32_bf16 v[32:35], v[168:171], v[188:191], v[32:35]
	v_mfma_f32_16x16x32_bf16 v[20:23], v[160:163], v[198:201], v[20:23]
	v_mfma_f32_16x16x32_bf16 v[16:19], v[168:171], v[198:201], v[16:19]
	v_mfma_f32_16x16x32_bf16 v[4:7], v[160:163], v[214:217], v[4:7]
	v_mfma_f32_16x16x32_bf16 v[0:3], v[168:171], v[214:217], v[0:3]
	s_setprio 0
	s_barrier
	s_add_i32 s40, 0, 0x18000
	s_add_i32 s44, 0, 0x1c000
	v_add_u32_e32 v140, s40, v178
	v_add_u32_e32 v168, s44, v178
	ds_read_b128 v[128:131], v140
	ds_read_b128 v[132:135], v140 offset:1024
	ds_read_b128 v[136:139], v140 offset:2048
	ds_read_b128 v[140:143], v140 offset:3072
	ds_read_b128 v[156:159], v168
	ds_read_b128 v[160:163], v168 offset:1024
	ds_read_b128 v[164:167], v168 offset:2048
	ds_read_b128 v[168:171], v168 offset:3072
	s_add_u32 s16, s16, 0x40000
	s_addc_u32 s17, s17, 0
	s_mov_b32 m0, s58
	v_lshl_add_u64 v[226:227], s[16:17], 0, v[150:151]
	ds_read_b128 v[172:175], v179 offset:32768
	ds_read_b128 v[180:183], v179 offset:33792
	ds_read_b128 v[184:187], v179 offset:34816
	ds_read_b128 v[188:191], v179 offset:35840
	ds_read_b128 v[194:197], v179 offset:36864
	ds_read_b128 v[198:201], v179 offset:37888
	ds_read_b128 v[202:205], v179 offset:38912
	ds_read_b128 v[214:217], v179 offset:39936
	global_load_lds_dwordx4 v[226:227], off
	v_lshl_add_u64 v[226:227], s[16:17], 0, v[146:147]
	s_mov_b32 m0, s59
	s_nop 0
	global_load_lds_dwordx4 v[226:227], off
	s_waitcnt vmcnt(8)
	s_waitcnt lgkmcnt(0)
	s_barrier
	s_setprio 1
	v_mfma_f32_16x16x32_bf16 v[124:127], v[128:131], v[172:175], v[124:127]
	v_mfma_f32_16x16x32_bf16 v[120:123], v[136:139], v[172:175], v[120:123]
	v_mfma_f32_16x16x32_bf16 v[108:111], v[128:131], v[184:187], v[108:111]
	v_mfma_f32_16x16x32_bf16 v[104:107], v[136:139], v[184:187], v[104:107]
	v_mfma_f32_16x16x32_bf16 v[92:95], v[128:131], v[194:197], v[92:95]
	v_mfma_f32_16x16x32_bf16 v[88:91], v[136:139], v[194:197], v[88:91]
	v_mfma_f32_16x16x32_bf16 v[76:79], v[128:131], v[202:205], v[76:79]
	v_mfma_f32_16x16x32_bf16 v[72:75], v[136:139], v[202:205], v[72:75]
	v_mfma_f32_16x16x32_bf16 v[124:127], v[132:135], v[180:183], v[124:127]
	v_mfma_f32_16x16x32_bf16 v[120:123], v[140:143], v[180:183], v[120:123]
	v_mfma_f32_16x16x32_bf16 v[108:111], v[132:135], v[188:191], v[108:111]
	v_mfma_f32_16x16x32_bf16 v[104:107], v[140:143], v[188:191], v[104:107]
	v_mfma_f32_16x16x32_bf16 v[92:95], v[132:135], v[198:201], v[92:95]
	v_mfma_f32_16x16x32_bf16 v[88:91], v[140:143], v[198:201], v[88:91]
	v_mfma_f32_16x16x32_bf16 v[76:79], v[132:135], v[214:217], v[76:79]
	v_mfma_f32_16x16x32_bf16 v[72:75], v[140:143], v[214:217], v[72:75]
	v_mfma_f32_16x16x32_bf16 v[116:119], v[156:159], v[172:175], v[116:119]
	v_mfma_f32_16x16x32_bf16 v[112:115], v[164:167], v[172:175], v[112:115]
	v_mfma_f32_16x16x32_bf16 v[100:103], v[156:159], v[184:187], v[100:103]
	v_mfma_f32_16x16x32_bf16 v[96:99], v[164:167], v[184:187], v[96:99]
	v_mfma_f32_16x16x32_bf16 v[84:87], v[156:159], v[194:197], v[84:87]
	v_mfma_f32_16x16x32_bf16 v[80:83], v[164:167], v[194:197], v[80:83]
	v_mfma_f32_16x16x32_bf16 v[68:71], v[156:159], v[202:205], v[68:71]
	v_mfma_f32_16x16x32_bf16 v[64:67], v[164:167], v[202:205], v[64:67]
	v_mfma_f32_16x16x32_bf16 v[116:119], v[160:163], v[180:183], v[116:119]
	v_mfma_f32_16x16x32_bf16 v[112:115], v[168:171], v[180:183], v[112:115]
	v_mfma_f32_16x16x32_bf16 v[100:103], v[160:163], v[188:191], v[100:103]
	v_mfma_f32_16x16x32_bf16 v[96:99], v[168:171], v[188:191], v[96:99]
	v_mfma_f32_16x16x32_bf16 v[84:87], v[160:163], v[198:201], v[84:87]
	v_mfma_f32_16x16x32_bf16 v[80:83], v[168:171], v[198:201], v[80:83]
	v_mfma_f32_16x16x32_bf16 v[68:71], v[160:163], v[214:217], v[68:71]
	v_mfma_f32_16x16x32_bf16 v[64:67], v[168:171], v[214:217], v[64:67]
	s_setprio 0
	s_barrier
	s_add_i32 s16, s40, s61
	v_lshl_add_u64 v[218:219], v[218:219], 0, s[76:77]
	s_mov_b32 m0, s16
	ds_read_b128 v[172:175], v179 offset:49152
	ds_read_b128 v[180:183], v179 offset:50176
	ds_read_b128 v[184:187], v179 offset:51200
	ds_read_b128 v[188:191], v179 offset:52224
	ds_read_b128 v[194:197], v179 offset:53248
	ds_read_b128 v[198:201], v179 offset:54272
	ds_read_b128 v[202:205], v179 offset:55296
	ds_read_b128 v[214:217], v179 offset:56320
	global_load_lds_dwordx4 v[218:219], off
	s_add_i32 m0, s16, 0x2000
	s_add_u32 s14, s14, 0x40080
	v_lshl_add_u64 v[218:219], v[220:221], 0, s[76:77]
	s_addc_u32 s15, s15, 0
	s_add_i32 s16, s44, s61
	global_load_lds_dwordx4 v[218:219], off
	v_lshl_add_u64 v[218:219], s[14:15], 0, v[148:149]
	s_mov_b32 m0, s16
	s_nop 0
	global_load_lds_dwordx4 v[218:219], off
	v_lshl_add_u64 v[218:219], s[14:15], 0, v[144:145]
	s_add_i32 m0, s16, 0x2000
	s_nop 0
	global_load_lds_dwordx4 v[218:219], off
	v_lshl_add_u64 v[218:219], v[222:223], 0, s[76:77]
	s_mov_b32 m0, s26
	s_nop 0
	global_load_lds_dwordx4 v[218:219], off
	v_lshl_add_u64 v[218:219], v[224:225], 0, s[76:77]
	s_mov_b32 m0, s27
	s_nop 0
	global_load_lds_dwordx4 v[218:219], off
	s_waitcnt vmcnt(8)
	s_waitcnt lgkmcnt(0)
	s_barrier
	s_setprio 1
	v_mfma_f32_16x16x32_bf16 v[60:63], v[128:131], v[172:175], v[60:63]
	v_mfma_f32_16x16x32_bf16 v[56:59], v[136:139], v[172:175], v[56:59]
	v_mfma_f32_16x16x32_bf16 v[44:47], v[128:131], v[184:187], v[44:47]
	v_mfma_f32_16x16x32_bf16 v[40:43], v[136:139], v[184:187], v[40:43]
	v_mfma_f32_16x16x32_bf16 v[28:31], v[128:131], v[194:197], v[28:31]
	v_mfma_f32_16x16x32_bf16 v[24:27], v[136:139], v[194:197], v[24:27]
	v_mfma_f32_16x16x32_bf16 v[12:15], v[128:131], v[202:205], v[12:15]
	v_mfma_f32_16x16x32_bf16 v[8:11], v[136:139], v[202:205], v[8:11]
	v_mfma_f32_16x16x32_bf16 v[60:63], v[132:135], v[180:183], v[60:63]
	v_mfma_f32_16x16x32_bf16 v[56:59], v[140:143], v[180:183], v[56:59]
	v_mfma_f32_16x16x32_bf16 v[44:47], v[132:135], v[188:191], v[44:47]
	v_mfma_f32_16x16x32_bf16 v[40:43], v[140:143], v[188:191], v[40:43]
	v_mfma_f32_16x16x32_bf16 v[28:31], v[132:135], v[198:201], v[28:31]
	v_mfma_f32_16x16x32_bf16 v[24:27], v[140:143], v[198:201], v[24:27]
	v_mfma_f32_16x16x32_bf16 v[12:15], v[132:135], v[214:217], v[12:15]
	v_mfma_f32_16x16x32_bf16 v[8:11], v[140:143], v[214:217], v[8:11]
	v_mfma_f32_16x16x32_bf16 v[52:55], v[156:159], v[172:175], v[52:55]
	v_mfma_f32_16x16x32_bf16 v[48:51], v[164:167], v[172:175], v[48:51]
	v_mfma_f32_16x16x32_bf16 v[36:39], v[156:159], v[184:187], v[36:39]
	v_mfma_f32_16x16x32_bf16 v[32:35], v[164:167], v[184:187], v[32:35]
	v_mfma_f32_16x16x32_bf16 v[20:23], v[156:159], v[194:197], v[20:23]
	v_mfma_f32_16x16x32_bf16 v[16:19], v[164:167], v[194:197], v[16:19]
	v_mfma_f32_16x16x32_bf16 v[4:7], v[156:159], v[202:205], v[4:7]
	v_mfma_f32_16x16x32_bf16 v[0:3], v[164:167], v[202:205], v[0:3]
	v_mfma_f32_16x16x32_bf16 v[52:55], v[160:163], v[180:183], v[52:55]
	v_mfma_f32_16x16x32_bf16 v[48:51], v[168:171], v[180:183], v[48:51]
	v_mfma_f32_16x16x32_bf16 v[36:39], v[160:163], v[188:191], v[36:39]
	v_mfma_f32_16x16x32_bf16 v[32:35], v[168:171], v[188:191], v[32:35]
	v_mfma_f32_16x16x32_bf16 v[20:23], v[160:163], v[198:201], v[20:23]
	v_mfma_f32_16x16x32_bf16 v[16:19], v[168:171], v[198:201], v[16:19]
	v_mfma_f32_16x16x32_bf16 v[4:7], v[160:163], v[214:217], v[4:7]
	v_mfma_f32_16x16x32_bf16 v[0:3], v[168:171], v[214:217], v[0:3]
	s_setprio 0
	s_barrier
	s_add_i32 s39, s39, 2
	s_add_u32 s33, s33, 0x100
	s_addc_u32 s38, s38, 0
	s_add_u32 s12, s12, 0x100
	s_addc_u32 s13, s13, 0
	s_cmp_gt_u32 s39, 13
	s_cbranch_scc0 .LBB0_299
	s_and_b64 vcc, exec, s[80:81]
	s_cbranch_vccz .LBB0_302
	s_barrier

.LBB0_650:
	s_add_u32 s24, s22, 0x100
	s_addc_u32 s25, s23, 0
	s_add_u32 s26, s19, s22
	s_addc_u32 s27, s63, s23
	s_cmp_eq_u32 s64, 4
	s_cselect_b32 s28, 0, s24
	s_cselect_b32 s29, 0, s25
	s_cselect_b32 s26, s13, s26
	s_cselect_b32 s27, s11, s27
	s_add_u32 s28, s2, s28
	s_addc_u32 s29, s3, s29
	s_add_i32 s65, 0, 0x10000
	s_add_i32 s66, 0, 0x14000
	v_add_u32_e32 v140, s65, v166
	v_add_u32_e32 v172, s66, v166
	ds_read_b128 v[128:131], v140
	ds_read_b128 v[132:135], v140 offset:1024
	ds_read_b128 v[136:139], v140 offset:2048
	ds_read_b128 v[140:143], v140 offset:3072
	ds_read_b128 v[144:147], v172
	ds_read_b128 v[148:151], v172 offset:1024
	ds_read_b128 v[168:171], v172 offset:2048
	ds_read_b128 v[172:175], v172 offset:3072
	v_lshl_add_u64 v[218:219], v[162:163], 0, s[22:23]
	s_add_i32 m0, s21, 0xc000
	ds_read_b128 v[176:179], v167
	ds_read_b128 v[180:183], v167 offset:1024
	ds_read_b128 v[184:187], v167 offset:2048
	ds_read_b128 v[188:191], v167 offset:3072
	ds_read_b128 v[194:197], v167 offset:4096
	ds_read_b128 v[198:201], v167 offset:5120
	ds_read_b128 v[202:205], v167 offset:6144
	ds_read_b128 v[214:217], v167 offset:7168
	global_load_lds_dwordx4 v[218:219], off
	v_lshl_add_u64 v[218:219], v[160:161], 0, s[22:23]
	s_add_i32 m0, s21, 0xe000
	s_nop 0
	global_load_lds_dwordx4 v[218:219], off
	s_waitcnt vmcnt(8)
	s_waitcnt lgkmcnt(0)
	s_barrier
	s_setprio 1
	v_mfma_f32_16x16x32_bf16 v[124:127], v[128:131], v[176:179], v[124:127]
	v_mfma_f32_16x16x32_bf16 v[120:123], v[136:139], v[176:179], v[120:123]
	v_mfma_f32_16x16x32_bf16 v[108:111], v[128:131], v[184:187], v[108:111]
	v_mfma_f32_16x16x32_bf16 v[104:107], v[136:139], v[184:187], v[104:107]
	v_mfma_f32_16x16x32_bf16 v[96:99], v[128:131], v[194:197], v[96:99]
	v_mfma_f32_16x16x32_bf16 v[88:91], v[136:139], v[194:197], v[88:91]
	v_mfma_f32_16x16x32_bf16 v[80:83], v[128:131], v[202:205], v[80:83]
	v_mfma_f32_16x16x32_bf16 v[72:75], v[136:139], v[202:205], v[72:75]
	v_mfma_f32_16x16x32_bf16 v[124:127], v[132:135], v[180:183], v[124:127]
	v_mfma_f32_16x16x32_bf16 v[120:123], v[140:143], v[180:183], v[120:123]
	v_mfma_f32_16x16x32_bf16 v[108:111], v[132:135], v[188:191], v[108:111]
	v_mfma_f32_16x16x32_bf16 v[104:107], v[140:143], v[188:191], v[104:107]
	v_mfma_f32_16x16x32_bf16 v[96:99], v[132:135], v[198:201], v[96:99]
	v_mfma_f32_16x16x32_bf16 v[88:91], v[140:143], v[198:201], v[88:91]
	v_mfma_f32_16x16x32_bf16 v[80:83], v[132:135], v[214:217], v[80:83]
	v_mfma_f32_16x16x32_bf16 v[72:75], v[140:143], v[214:217], v[72:75]
	v_mfma_f32_16x16x32_bf16 v[116:119], v[144:147], v[176:179], v[116:119]
	v_mfma_f32_16x16x32_bf16 v[112:115], v[168:171], v[176:179], v[112:115]
	v_mfma_f32_16x16x32_bf16 v[100:103], v[144:147], v[184:187], v[100:103]
	v_mfma_f32_16x16x32_bf16 v[92:95], v[168:171], v[184:187], v[92:95]
	v_mfma_f32_16x16x32_bf16 v[84:87], v[144:147], v[194:197], v[84:87]
	v_mfma_f32_16x16x32_bf16 v[76:79], v[168:171], v[194:197], v[76:79]
	v_mfma_f32_16x16x32_bf16 v[68:71], v[144:147], v[202:205], v[68:71]
	v_mfma_f32_16x16x32_bf16 v[64:67], v[168:171], v[202:205], v[64:67]
	v_mfma_f32_16x16x32_bf16 v[116:119], v[148:151], v[180:183], v[116:119]
	v_mfma_f32_16x16x32_bf16 v[112:115], v[172:175], v[180:183], v[112:115]
	v_mfma_f32_16x16x32_bf16 v[100:103], v[148:151], v[188:191], v[100:103]
	v_mfma_f32_16x16x32_bf16 v[92:95], v[172:175], v[188:191], v[92:95]
	v_mfma_f32_16x16x32_bf16 v[84:87], v[148:151], v[198:201], v[84:87]
	v_mfma_f32_16x16x32_bf16 v[76:79], v[172:175], v[198:201], v[76:79]
	v_mfma_f32_16x16x32_bf16 v[68:71], v[148:151], v[214:217], v[68:71]
	v_mfma_f32_16x16x32_bf16 v[64:67], v[172:175], v[214:217], v[64:67]
	s_setprio 0
	s_barrier
	s_add_i32 s22, s65, s35
	v_lshl_add_u64 v[218:219], s[26:27], 0, v[156:157]
	s_mov_b32 m0, s22
	ds_read_b128 v[176:179], v167 offset:16384
	ds_read_b128 v[180:183], v167 offset:17408
	ds_read_b128 v[184:187], v167 offset:18432
	ds_read_b128 v[188:191], v167 offset:19456
	ds_read_b128 v[194:197], v167 offset:20480
	ds_read_b128 v[198:201], v167 offset:21504
	ds_read_b128 v[202:205], v167 offset:22528
	ds_read_b128 v[214:217], v167 offset:23552
	global_load_lds_dwordx4 v[218:219], off
	s_add_i32 m0, s22, 0x2000
	s_add_u32 s22, s26, 0x20000
	v_lshl_add_u64 v[220:221], s[26:27], 0, v[152:153]
	s_addc_u32 s23, s27, 0
	s_add_i32 s65, s66, s35
	global_load_lds_dwordx4 v[220:221], off
	v_lshl_add_u64 v[222:223], s[22:23], 0, v[156:157]
	s_mov_b32 m0, s65
	v_lshl_add_u64 v[224:225], s[28:29], 0, v[154:155]
	global_load_lds_dwordx4 v[222:223], off
	v_lshl_add_u64 v[222:223], s[22:23], 0, v[152:153]
	s_add_i32 m0, s65, 0x2000
	s_nop 0
	global_load_lds_dwordx4 v[222:223], off
	v_lshl_add_u64 v[222:223], s[28:29], 0, v[158:159]
	s_mov_b32 m0, s21
	s_nop 0
	global_load_lds_dwordx4 v[222:223], off
	s_mov_b32 m0, s36
	s_nop 0
	global_load_lds_dwordx4 v[224:225], off
	s_waitcnt vmcnt(8)
	s_waitcnt lgkmcnt(0)
	s_barrier
	s_setprio 1
	v_mfma_f32_16x16x32_bf16 v[60:63], v[128:131], v[176:179], v[60:63]
	v_mfma_f32_16x16x32_bf16 v[56:59], v[136:139], v[176:179], v[56:59]
	v_mfma_f32_16x16x32_bf16 v[48:51], v[128:131], v[184:187], v[48:51]
	v_mfma_f32_16x16x32_bf16 v[40:43], v[136:139], v[184:187], v[40:43]
	v_mfma_f32_16x16x32_bf16 v[32:35], v[128:131], v[194:197], v[32:35]
	v_mfma_f32_16x16x32_bf16 v[24:27], v[136:139], v[194:197], v[24:27]
	v_mfma_f32_16x16x32_bf16 v[16:19], v[128:131], v[202:205], v[16:19]
	v_mfma_f32_16x16x32_bf16 v[8:11], v[136:139], v[202:205], v[8:11]
	v_mfma_f32_16x16x32_bf16 v[60:63], v[132:135], v[180:183], v[60:63]
	v_mfma_f32_16x16x32_bf16 v[56:59], v[140:143], v[180:183], v[56:59]
	v_mfma_f32_16x16x32_bf16 v[48:51], v[132:135], v[188:191], v[48:51]
	v_mfma_f32_16x16x32_bf16 v[40:43], v[140:143], v[188:191], v[40:43]
	v_mfma_f32_16x16x32_bf16 v[32:35], v[132:135], v[198:201], v[32:35]
	v_mfma_f32_16x16x32_bf16 v[24:27], v[140:143], v[198:201], v[24:27]
	v_mfma_f32_16x16x32_bf16 v[16:19], v[132:135], v[214:217], v[16:19]
	v_mfma_f32_16x16x32_bf16 v[8:11], v[140:143], v[214:217], v[8:11]
	v_mfma_f32_16x16x32_bf16 v[52:55], v[144:147], v[176:179], v[52:55]
	v_mfma_f32_16x16x32_bf16 v[44:47], v[168:171], v[176:179], v[44:47]
	v_mfma_f32_16x16x32_bf16 v[36:39], v[144:147], v[184:187], v[36:39]
	v_mfma_f32_16x16x32_bf16 v[28:31], v[168:171], v[184:187], v[28:31]
	v_mfma_f32_16x16x32_bf16 v[20:23], v[144:147], v[194:197], v[20:23]
	v_mfma_f32_16x16x32_bf16 v[12:15], v[168:171], v[194:197], v[12:15]
	v_mfma_f32_16x16x32_bf16 v[4:7], v[144:147], v[202:205], v[4:7]
	v_mfma_f32_16x16x32_bf16 v[0:3], v[168:171], v[202:205], v[0:3]
	v_mfma_f32_16x16x32_bf16 v[52:55], v[148:151], v[180:183], v[52:55]
	v_mfma_f32_16x16x32_bf16 v[44:47], v[172:175], v[180:183], v[44:47]
	v_mfma_f32_16x16x32_bf16 v[36:39], v[148:151], v[188:191], v[36:39]
	v_mfma_f32_16x16x32_bf16 v[28:31], v[172:175], v[188:191], v[28:31]
	v_mfma_f32_16x16x32_bf16 v[20:23], v[148:151], v[198:201], v[20:23]
	v_mfma_f32_16x16x32_bf16 v[12:15], v[172:175], v[198:201], v[12:15]
	v_mfma_f32_16x16x32_bf16 v[4:7], v[148:151], v[214:217], v[4:7]
	v_mfma_f32_16x16x32_bf16 v[0:3], v[172:175], v[214:217], v[0:3]
	s_setprio 0
	s_barrier
	s_add_i32 s65, 0, 0x18000
	s_add_i32 s66, 0, 0x1c000
	v_add_u32_e32 v140, s65, v166
	v_add_u32_e32 v172, s66, v166
	ds_read_b128 v[128:131], v140
	ds_read_b128 v[132:135], v140 offset:1024
	ds_read_b128 v[136:139], v140 offset:2048
	ds_read_b128 v[140:143], v140 offset:3072
	ds_read_b128 v[144:147], v172
	ds_read_b128 v[148:151], v172 offset:1024
	ds_read_b128 v[168:171], v172 offset:2048
	ds_read_b128 v[172:175], v172 offset:3072
	s_add_u32 s22, s28, 0x20000
	s_addc_u32 s23, s29, 0
	s_mov_b32 m0, s37
	v_lshl_add_u64 v[226:227], s[22:23], 0, v[158:159]
	ds_read_b128 v[176:179], v167 offset:32768
	ds_read_b128 v[180:183], v167 offset:33792
	ds_read_b128 v[184:187], v167 offset:34816
	ds_read_b128 v[188:191], v167 offset:35840
	ds_read_b128 v[194:197], v167 offset:36864
	ds_read_b128 v[198:201], v167 offset:37888
	ds_read_b128 v[202:205], v167 offset:38912
	ds_read_b128 v[214:217], v167 offset:39936
	global_load_lds_dwordx4 v[226:227], off
	v_lshl_add_u64 v[226:227], s[22:23], 0, v[154:155]
	s_mov_b32 m0, s38
	s_nop 0
	global_load_lds_dwordx4 v[226:227], off
	s_waitcnt vmcnt(8)
	s_waitcnt lgkmcnt(0)
	s_barrier
	s_setprio 1
	v_mfma_f32_16x16x32_bf16 v[124:127], v[128:131], v[176:179], v[124:127]
	v_mfma_f32_16x16x32_bf16 v[120:123], v[136:139], v[176:179], v[120:123]
	v_mfma_f32_16x16x32_bf16 v[108:111], v[128:131], v[184:187], v[108:111]
	v_mfma_f32_16x16x32_bf16 v[104:107], v[136:139], v[184:187], v[104:107]
	v_mfma_f32_16x16x32_bf16 v[96:99], v[128:131], v[194:197], v[96:99]
	v_mfma_f32_16x16x32_bf16 v[88:91], v[136:139], v[194:197], v[88:91]
	v_mfma_f32_16x16x32_bf16 v[80:83], v[128:131], v[202:205], v[80:83]
	v_mfma_f32_16x16x32_bf16 v[72:75], v[136:139], v[202:205], v[72:75]
	v_mfma_f32_16x16x32_bf16 v[124:127], v[132:135], v[180:183], v[124:127]
	v_mfma_f32_16x16x32_bf16 v[120:123], v[140:143], v[180:183], v[120:123]
	v_mfma_f32_16x16x32_bf16 v[108:111], v[132:135], v[188:191], v[108:111]
	v_mfma_f32_16x16x32_bf16 v[104:107], v[140:143], v[188:191], v[104:107]
	v_mfma_f32_16x16x32_bf16 v[96:99], v[132:135], v[198:201], v[96:99]
	v_mfma_f32_16x16x32_bf16 v[88:91], v[140:143], v[198:201], v[88:91]
	v_mfma_f32_16x16x32_bf16 v[80:83], v[132:135], v[214:217], v[80:83]
	v_mfma_f32_16x16x32_bf16 v[72:75], v[140:143], v[214:217], v[72:75]
	v_mfma_f32_16x16x32_bf16 v[116:119], v[144:147], v[176:179], v[116:119]
	v_mfma_f32_16x16x32_bf16 v[112:115], v[168:171], v[176:179], v[112:115]
	v_mfma_f32_16x16x32_bf16 v[100:103], v[144:147], v[184:187], v[100:103]
	v_mfma_f32_16x16x32_bf16 v[92:95], v[168:171], v[184:187], v[92:95]
	v_mfma_f32_16x16x32_bf16 v[84:87], v[144:147], v[194:197], v[84:87]
	v_mfma_f32_16x16x32_bf16 v[76:79], v[168:171], v[194:197], v[76:79]
	v_mfma_f32_16x16x32_bf16 v[68:71], v[144:147], v[202:205], v[68:71]
	v_mfma_f32_16x16x32_bf16 v[64:67], v[168:171], v[202:205], v[64:67]
	v_mfma_f32_16x16x32_bf16 v[116:119], v[148:151], v[180:183], v[116:119]
	v_mfma_f32_16x16x32_bf16 v[112:115], v[172:175], v[180:183], v[112:115]
	v_mfma_f32_16x16x32_bf16 v[100:103], v[148:151], v[188:191], v[100:103]
	v_mfma_f32_16x16x32_bf16 v[92:95], v[172:175], v[188:191], v[92:95]
	v_mfma_f32_16x16x32_bf16 v[84:87], v[148:151], v[198:201], v[84:87]
	v_mfma_f32_16x16x32_bf16 v[76:79], v[172:175], v[198:201], v[76:79]
	v_mfma_f32_16x16x32_bf16 v[68:71], v[148:151], v[214:217], v[68:71]
	v_mfma_f32_16x16x32_bf16 v[64:67], v[172:175], v[214:217], v[64:67]
	s_setprio 0
	s_barrier
	s_add_i32 s22, s65, s35
	v_lshl_add_u64 v[218:219], v[218:219], 0, s[76:77]
	s_mov_b32 m0, s22
	ds_read_b128 v[176:179], v167 offset:49152
	ds_read_b128 v[180:183], v167 offset:50176
	ds_read_b128 v[184:187], v167 offset:51200
	ds_read_b128 v[188:191], v167 offset:52224
	ds_read_b128 v[194:197], v167 offset:53248
	ds_read_b128 v[198:201], v167 offset:54272
	ds_read_b128 v[202:205], v167 offset:55296
	ds_read_b128 v[214:217], v167 offset:56320
	global_load_lds_dwordx4 v[218:219], off
	s_add_i32 m0, s22, 0x2000
	s_add_u32 s22, s26, 0x20080
	v_lshl_add_u64 v[218:219], v[220:221], 0, s[76:77]
	s_addc_u32 s23, s27, 0
	s_add_i32 s26, s66, s35
	global_load_lds_dwordx4 v[218:219], off
	v_lshl_add_u64 v[218:219], s[22:23], 0, v[156:157]
	s_mov_b32 m0, s26
	s_nop 0
	global_load_lds_dwordx4 v[218:219], off
	v_lshl_add_u64 v[218:219], s[22:23], 0, v[152:153]
	s_add_i32 m0, s26, 0x2000
	s_nop 0
	global_load_lds_dwordx4 v[218:219], off
	v_lshl_add_u64 v[218:219], v[222:223], 0, s[76:77]
	s_mov_b32 m0, s44
	s_nop 0
	global_load_lds_dwordx4 v[218:219], off
	v_lshl_add_u64 v[218:219], v[224:225], 0, s[76:77]
	s_mov_b32 m0, s45
	s_nop 0
	global_load_lds_dwordx4 v[218:219], off
	s_waitcnt vmcnt(8)
	s_waitcnt lgkmcnt(0)
	s_barrier
	s_setprio 1
	v_mfma_f32_16x16x32_bf16 v[60:63], v[128:131], v[176:179], v[60:63]
	v_mfma_f32_16x16x32_bf16 v[56:59], v[136:139], v[176:179], v[56:59]
	v_mfma_f32_16x16x32_bf16 v[48:51], v[128:131], v[184:187], v[48:51]
	v_mfma_f32_16x16x32_bf16 v[40:43], v[136:139], v[184:187], v[40:43]
	v_mfma_f32_16x16x32_bf16 v[32:35], v[128:131], v[194:197], v[32:35]
	v_mfma_f32_16x16x32_bf16 v[24:27], v[136:139], v[194:197], v[24:27]
	v_mfma_f32_16x16x32_bf16 v[16:19], v[128:131], v[202:205], v[16:19]
	v_mfma_f32_16x16x32_bf16 v[8:11], v[136:139], v[202:205], v[8:11]
	v_mfma_f32_16x16x32_bf16 v[60:63], v[132:135], v[180:183], v[60:63]
	v_mfma_f32_16x16x32_bf16 v[56:59], v[140:143], v[180:183], v[56:59]
	v_mfma_f32_16x16x32_bf16 v[48:51], v[132:135], v[188:191], v[48:51]
	v_mfma_f32_16x16x32_bf16 v[40:43], v[140:143], v[188:191], v[40:43]
	v_mfma_f32_16x16x32_bf16 v[32:35], v[132:135], v[198:201], v[32:35]
	v_mfma_f32_16x16x32_bf16 v[24:27], v[140:143], v[198:201], v[24:27]
	v_mfma_f32_16x16x32_bf16 v[16:19], v[132:135], v[214:217], v[16:19]
	v_mfma_f32_16x16x32_bf16 v[8:11], v[140:143], v[214:217], v[8:11]
	v_mfma_f32_16x16x32_bf16 v[52:55], v[144:147], v[176:179], v[52:55]
	v_mfma_f32_16x16x32_bf16 v[44:47], v[168:171], v[176:179], v[44:47]
	v_mfma_f32_16x16x32_bf16 v[36:39], v[144:147], v[184:187], v[36:39]
	v_mfma_f32_16x16x32_bf16 v[28:31], v[168:171], v[184:187], v[28:31]
	v_mfma_f32_16x16x32_bf16 v[20:23], v[144:147], v[194:197], v[20:23]
	v_mfma_f32_16x16x32_bf16 v[12:15], v[168:171], v[194:197], v[12:15]
	v_mfma_f32_16x16x32_bf16 v[4:7], v[144:147], v[202:205], v[4:7]
	v_mfma_f32_16x16x32_bf16 v[0:3], v[168:171], v[202:205], v[0:3]
	v_mfma_f32_16x16x32_bf16 v[52:55], v[148:151], v[180:183], v[52:55]
	v_mfma_f32_16x16x32_bf16 v[44:47], v[172:175], v[180:183], v[44:47]
	v_mfma_f32_16x16x32_bf16 v[36:39], v[148:151], v[188:191], v[36:39]
	v_mfma_f32_16x16x32_bf16 v[28:31], v[172:175], v[188:191], v[28:31]
	v_mfma_f32_16x16x32_bf16 v[20:23], v[148:151], v[198:201], v[20:23]
	v_mfma_f32_16x16x32_bf16 v[12:15], v[172:175], v[198:201], v[12:15]
	v_mfma_f32_16x16x32_bf16 v[4:7], v[148:151], v[214:217], v[4:7]
	v_mfma_f32_16x16x32_bf16 v[0:3], v[172:175], v[214:217], v[0:3]
	s_setprio 0
	s_barrier
	s_add_i32 s64, s64, 2
	s_cmp_gt_u32 s64, 5
	s_mov_b64 s[22:23], s[24:25]
	s_cbranch_scc0 .LBB0_650
	s_and_b64 vcc, exec, s[8:9]
	s_cbranch_vccz .LBB0_653
	s_barrier

.LBB0_670:
	s_add_u32 s19, s24, 0xffe00080
	s_addc_u32 s26, s25, -1
	s_add_i32 s63, 0, 0x10000
	s_cmpk_eq_i32 s13, 0x7c
	s_cselect_b32 s29, s15, s26
	s_cselect_b32 s28, s14, s19
	s_cselect_b32 s27, s17, s11
	s_cselect_b32 s26, s16, s9
	s_add_i32 s19, 0, 0x14000
	v_add_u32_e32 v140, s63, v170
	v_add_u32_e32 v172, s19, v170
	ds_read_b128 v[128:131], v140
	ds_read_b128 v[132:135], v140 offset:1024
	ds_read_b128 v[136:139], v140 offset:2048
	ds_read_b128 v[140:143], v140 offset:3072
	ds_read_b128 v[144:147], v172
	ds_read_b128 v[148:151], v172 offset:1024
	ds_read_b128 v[152:155], v172 offset:2048
	ds_read_b128 v[172:175], v172 offset:3072
	v_lshl_add_u64 v[218:219], s[24:25], 0, v[166:167]
	s_add_i32 m0, s23, 0xc000
	ds_read_b128 v[176:179], v171
	ds_read_b128 v[180:183], v171 offset:1024
	ds_read_b128 v[184:187], v171 offset:2048
	ds_read_b128 v[188:191], v171 offset:3072
	ds_read_b128 v[194:197], v171 offset:4096
	ds_read_b128 v[198:201], v171 offset:5120
	ds_read_b128 v[202:205], v171 offset:6144
	ds_read_b128 v[214:217], v171 offset:7168
	global_load_lds_dwordx4 v[218:219], off
	v_lshl_add_u64 v[218:219], s[24:25], 0, v[164:165]
	s_add_i32 m0, s23, 0xe000
	s_nop 0
	global_load_lds_dwordx4 v[218:219], off
	s_waitcnt vmcnt(8)
	s_waitcnt lgkmcnt(0)
	s_barrier
	s_setprio 1
	v_mfma_f32_16x16x32_bf16 v[124:127], v[128:131], v[176:179], v[124:127]
	v_mfma_f32_16x16x32_bf16 v[120:123], v[136:139], v[176:179], v[120:123]
	v_mfma_f32_16x16x32_bf16 v[108:111], v[128:131], v[184:187], v[108:111]
	v_mfma_f32_16x16x32_bf16 v[104:107], v[136:139], v[184:187], v[104:107]
	v_mfma_f32_16x16x32_bf16 v[96:99], v[128:131], v[194:197], v[96:99]
	v_mfma_f32_16x16x32_bf16 v[88:91], v[136:139], v[194:197], v[88:91]
	v_mfma_f32_16x16x32_bf16 v[80:83], v[128:131], v[202:205], v[80:83]
	v_mfma_f32_16x16x32_bf16 v[72:75], v[136:139], v[202:205], v[72:75]
	v_mfma_f32_16x16x32_bf16 v[124:127], v[132:135], v[180:183], v[124:127]
	v_mfma_f32_16x16x32_bf16 v[120:123], v[140:143], v[180:183], v[120:123]
	v_mfma_f32_16x16x32_bf16 v[108:111], v[132:135], v[188:191], v[108:111]
	v_mfma_f32_16x16x32_bf16 v[104:107], v[140:143], v[188:191], v[104:107]
	v_mfma_f32_16x16x32_bf16 v[96:99], v[132:135], v[198:201], v[96:99]
	v_mfma_f32_16x16x32_bf16 v[88:91], v[140:143], v[198:201], v[88:91]
	v_mfma_f32_16x16x32_bf16 v[80:83], v[132:135], v[214:217], v[80:83]
	v_mfma_f32_16x16x32_bf16 v[72:75], v[140:143], v[214:217], v[72:75]
	v_mfma_f32_16x16x32_bf16 v[116:119], v[144:147], v[176:179], v[116:119]
	v_mfma_f32_16x16x32_bf16 v[112:115], v[152:155], v[176:179], v[112:115]
	v_mfma_f32_16x16x32_bf16 v[100:103], v[144:147], v[184:187], v[100:103]
	v_mfma_f32_16x16x32_bf16 v[92:95], v[152:155], v[184:187], v[92:95]
	v_mfma_f32_16x16x32_bf16 v[84:87], v[144:147], v[194:197], v[84:87]
	v_mfma_f32_16x16x32_bf16 v[76:79], v[152:155], v[194:197], v[76:79]
	v_mfma_f32_16x16x32_bf16 v[68:71], v[144:147], v[202:205], v[68:71]
	v_mfma_f32_16x16x32_bf16 v[64:67], v[152:155], v[202:205], v[64:67]
	v_mfma_f32_16x16x32_bf16 v[116:119], v[148:151], v[180:183], v[116:119]
	v_mfma_f32_16x16x32_bf16 v[112:115], v[172:175], v[180:183], v[112:115]
	v_mfma_f32_16x16x32_bf16 v[100:103], v[148:151], v[188:191], v[100:103]
	v_mfma_f32_16x16x32_bf16 v[92:95], v[172:175], v[188:191], v[92:95]
	v_mfma_f32_16x16x32_bf16 v[84:87], v[148:151], v[198:201], v[84:87]
	v_mfma_f32_16x16x32_bf16 v[76:79], v[172:175], v[198:201], v[76:79]
	v_mfma_f32_16x16x32_bf16 v[68:71], v[148:151], v[214:217], v[68:71]
	v_mfma_f32_16x16x32_bf16 v[64:67], v[172:175], v[214:217], v[64:67]
	s_setprio 0
	s_barrier
	s_add_i32 s63, s63, s36
	v_lshl_add_u64 v[218:219], s[26:27], 0, v[160:161]
	s_mov_b32 m0, s63
	ds_read_b128 v[176:179], v171 offset:16384
	ds_read_b128 v[180:183], v171 offset:17408
	ds_read_b128 v[184:187], v171 offset:18432
	ds_read_b128 v[188:191], v171 offset:19456
	ds_read_b128 v[194:197], v171 offset:20480
	ds_read_b128 v[198:201], v171 offset:21504
	ds_read_b128 v[202:205], v171 offset:22528
	ds_read_b128 v[214:217], v171 offset:23552
	global_load_lds_dwordx4 v[218:219], off
	s_add_i32 m0, s63, 0x2000
	s_add_u32 s64, s26, 0x200000
	v_lshl_add_u64 v[220:221], s[26:27], 0, v[156:157]
	s_addc_u32 s65, s27, 0
	s_add_i32 s19, s19, s36
	global_load_lds_dwordx4 v[220:221], off
	v_lshl_add_u64 v[222:223], s[64:65], 0, v[160:161]
	s_mov_b32 m0, s19
	v_lshl_add_u64 v[224:225], s[28:29], 0, v[158:159]
	global_load_lds_dwordx4 v[222:223], off
	v_lshl_add_u64 v[222:223], s[64:65], 0, v[156:157]
	s_add_i32 m0, s19, 0x2000
	s_nop 0
	global_load_lds_dwordx4 v[222:223], off
	v_lshl_add_u64 v[222:223], s[28:29], 0, v[162:163]
	s_mov_b32 m0, s23
	s_nop 0
	global_load_lds_dwordx4 v[222:223], off
	s_mov_b32 m0, s21
	s_nop 0
	global_load_lds_dwordx4 v[224:225], off
	s_waitcnt vmcnt(8)
	s_waitcnt lgkmcnt(0)
	s_barrier
	s_setprio 1
	v_mfma_f32_16x16x32_bf16 v[60:63], v[128:131], v[176:179], v[60:63]
	v_mfma_f32_16x16x32_bf16 v[56:59], v[136:139], v[176:179], v[56:59]
	v_mfma_f32_16x16x32_bf16 v[48:51], v[128:131], v[184:187], v[48:51]
	v_mfma_f32_16x16x32_bf16 v[40:43], v[136:139], v[184:187], v[40:43]
	v_mfma_f32_16x16x32_bf16 v[32:35], v[128:131], v[194:197], v[32:35]
	v_mfma_f32_16x16x32_bf16 v[24:27], v[136:139], v[194:197], v[24:27]
	v_mfma_f32_16x16x32_bf16 v[16:19], v[128:131], v[202:205], v[16:19]
	v_mfma_f32_16x16x32_bf16 v[8:11], v[136:139], v[202:205], v[8:11]
	v_mfma_f32_16x16x32_bf16 v[60:63], v[132:135], v[180:183], v[60:63]
	v_mfma_f32_16x16x32_bf16 v[56:59], v[140:143], v[180:183], v[56:59]
	v_mfma_f32_16x16x32_bf16 v[48:51], v[132:135], v[188:191], v[48:51]
	v_mfma_f32_16x16x32_bf16 v[40:43], v[140:143], v[188:191], v[40:43]
	v_mfma_f32_16x16x32_bf16 v[32:35], v[132:135], v[198:201], v[32:35]
	v_mfma_f32_16x16x32_bf16 v[24:27], v[140:143], v[198:201], v[24:27]
	v_mfma_f32_16x16x32_bf16 v[16:19], v[132:135], v[214:217], v[16:19]
	v_mfma_f32_16x16x32_bf16 v[8:11], v[140:143], v[214:217], v[8:11]
	v_mfma_f32_16x16x32_bf16 v[52:55], v[144:147], v[176:179], v[52:55]
	v_mfma_f32_16x16x32_bf16 v[44:47], v[152:155], v[176:179], v[44:47]
	v_mfma_f32_16x16x32_bf16 v[36:39], v[144:147], v[184:187], v[36:39]
	v_mfma_f32_16x16x32_bf16 v[28:31], v[152:155], v[184:187], v[28:31]
	v_mfma_f32_16x16x32_bf16 v[20:23], v[144:147], v[194:197], v[20:23]
	v_mfma_f32_16x16x32_bf16 v[12:15], v[152:155], v[194:197], v[12:15]
	v_mfma_f32_16x16x32_bf16 v[4:7], v[144:147], v[202:205], v[4:7]
	v_mfma_f32_16x16x32_bf16 v[0:3], v[152:155], v[202:205], v[0:3]
	v_mfma_f32_16x16x32_bf16 v[52:55], v[148:151], v[180:183], v[52:55]
	v_mfma_f32_16x16x32_bf16 v[44:47], v[172:175], v[180:183], v[44:47]
	v_mfma_f32_16x16x32_bf16 v[36:39], v[148:151], v[188:191], v[36:39]
	v_mfma_f32_16x16x32_bf16 v[28:31], v[172:175], v[188:191], v[28:31]
	v_mfma_f32_16x16x32_bf16 v[20:23], v[148:151], v[198:201], v[20:23]
	v_mfma_f32_16x16x32_bf16 v[12:15], v[172:175], v[198:201], v[12:15]
	v_mfma_f32_16x16x32_bf16 v[4:7], v[148:151], v[214:217], v[4:7]
	v_mfma_f32_16x16x32_bf16 v[0:3], v[172:175], v[214:217], v[0:3]
	s_setprio 0
	s_barrier
	s_add_i32 s19, 0, 0x18000
	s_add_i32 s63, 0, 0x1c000
	v_add_u32_e32 v140, s19, v170
	v_add_u32_e32 v172, s63, v170
	ds_read_b128 v[128:131], v140
	ds_read_b128 v[132:135], v140 offset:1024
	ds_read_b128 v[136:139], v140 offset:2048
	ds_read_b128 v[140:143], v140 offset:3072
	ds_read_b128 v[144:147], v172
	ds_read_b128 v[148:151], v172 offset:1024
	ds_read_b128 v[152:155], v172 offset:2048
	ds_read_b128 v[172:175], v172 offset:3072
	s_add_u32 s28, s28, 0x200000
	s_addc_u32 s29, s29, 0
	s_mov_b32 m0, s37
	v_lshl_add_u64 v[226:227], s[28:29], 0, v[162:163]
	ds_read_b128 v[176:179], v171 offset:32768
	ds_read_b128 v[180:183], v171 offset:33792
	ds_read_b128 v[184:187], v171 offset:34816
	ds_read_b128 v[188:191], v171 offset:35840
	ds_read_b128 v[194:197], v171 offset:36864
	ds_read_b128 v[198:201], v171 offset:37888
	ds_read_b128 v[202:205], v171 offset:38912
	ds_read_b128 v[214:217], v171 offset:39936
	global_load_lds_dwordx4 v[226:227], off
	v_lshl_add_u64 v[226:227], s[28:29], 0, v[158:159]
	s_mov_b32 m0, s38
	s_nop 0
	global_load_lds_dwordx4 v[226:227], off
	s_waitcnt vmcnt(8)
	s_waitcnt lgkmcnt(0)
	s_barrier
	s_setprio 1
	v_mfma_f32_16x16x32_bf16 v[124:127], v[128:131], v[176:179], v[124:127]
	v_mfma_f32_16x16x32_bf16 v[120:123], v[136:139], v[176:179], v[120:123]
	v_mfma_f32_16x16x32_bf16 v[108:111], v[128:131], v[184:187], v[108:111]
	v_mfma_f32_16x16x32_bf16 v[104:107], v[136:139], v[184:187], v[104:107]
	v_mfma_f32_16x16x32_bf16 v[96:99], v[128:131], v[194:197], v[96:99]
	v_mfma_f32_16x16x32_bf16 v[88:91], v[136:139], v[194:197], v[88:91]
	v_mfma_f32_16x16x32_bf16 v[80:83], v[128:131], v[202:205], v[80:83]
	v_mfma_f32_16x16x32_bf16 v[72:75], v[136:139], v[202:205], v[72:75]
	v_mfma_f32_16x16x32_bf16 v[124:127], v[132:135], v[180:183], v[124:127]
	v_mfma_f32_16x16x32_bf16 v[120:123], v[140:143], v[180:183], v[120:123]
	v_mfma_f32_16x16x32_bf16 v[108:111], v[132:135], v[188:191], v[108:111]
	v_mfma_f32_16x16x32_bf16 v[104:107], v[140:143], v[188:191], v[104:107]
	v_mfma_f32_16x16x32_bf16 v[96:99], v[132:135], v[198:201], v[96:99]
	v_mfma_f32_16x16x32_bf16 v[88:91], v[140:143], v[198:201], v[88:91]
	v_mfma_f32_16x16x32_bf16 v[80:83], v[132:135], v[214:217], v[80:83]
	v_mfma_f32_16x16x32_bf16 v[72:75], v[140:143], v[214:217], v[72:75]
	v_mfma_f32_16x16x32_bf16 v[116:119], v[144:147], v[176:179], v[116:119]
	v_mfma_f32_16x16x32_bf16 v[112:115], v[152:155], v[176:179], v[112:115]
	v_mfma_f32_16x16x32_bf16 v[100:103], v[144:147], v[184:187], v[100:103]
	v_mfma_f32_16x16x32_bf16 v[92:95], v[152:155], v[184:187], v[92:95]
	v_mfma_f32_16x16x32_bf16 v[84:87], v[144:147], v[194:197], v[84:87]
	v_mfma_f32_16x16x32_bf16 v[76:79], v[152:155], v[194:197], v[76:79]
	v_mfma_f32_16x16x32_bf16 v[68:71], v[144:147], v[202:205], v[68:71]
	v_mfma_f32_16x16x32_bf16 v[64:67], v[152:155], v[202:205], v[64:67]
	v_mfma_f32_16x16x32_bf16 v[116:119], v[148:151], v[180:183], v[116:119]
	v_mfma_f32_16x16x32_bf16 v[112:115], v[172:175], v[180:183], v[112:115]
	v_mfma_f32_16x16x32_bf16 v[100:103], v[148:151], v[188:191], v[100:103]
	v_mfma_f32_16x16x32_bf16 v[92:95], v[172:175], v[188:191], v[92:95]
	v_mfma_f32_16x16x32_bf16 v[84:87], v[148:151], v[198:201], v[84:87]
	v_mfma_f32_16x16x32_bf16 v[76:79], v[172:175], v[198:201], v[76:79]
	v_mfma_f32_16x16x32_bf16 v[68:71], v[148:151], v[214:217], v[68:71]
	v_mfma_f32_16x16x32_bf16 v[64:67], v[172:175], v[214:217], v[64:67]
	s_setprio 0
	s_barrier
	s_add_i32 s19, s19, s36
	v_lshl_add_u64 v[218:219], v[218:219], 0, s[76:77]
	s_mov_b32 m0, s19
	ds_read_b128 v[176:179], v171 offset:49152
	ds_read_b128 v[180:183], v171 offset:50176
	ds_read_b128 v[184:187], v171 offset:51200
	ds_read_b128 v[188:191], v171 offset:52224
	ds_read_b128 v[194:197], v171 offset:53248
	ds_read_b128 v[198:201], v171 offset:54272
	ds_read_b128 v[202:205], v171 offset:55296
	ds_read_b128 v[214:217], v171 offset:56320
	global_load_lds_dwordx4 v[218:219], off
	s_add_i32 m0, s19, 0x2000
	s_add_u32 s26, s26, 0x200080
	v_lshl_add_u64 v[218:219], v[220:221], 0, s[76:77]
	s_addc_u32 s27, s27, 0
	s_add_i32 s19, s63, s36
	global_load_lds_dwordx4 v[218:219], off
	v_lshl_add_u64 v[218:219], s[26:27], 0, v[160:161]
	s_mov_b32 m0, s19
	s_nop 0
	global_load_lds_dwordx4 v[218:219], off
	v_lshl_add_u64 v[218:219], s[26:27], 0, v[156:157]
	s_add_i32 m0, s19, 0x2000
	s_nop 0
	global_load_lds_dwordx4 v[218:219], off
	v_lshl_add_u64 v[218:219], v[222:223], 0, s[76:77]
	s_mov_b32 m0, s44
	s_nop 0
	global_load_lds_dwordx4 v[218:219], off
	v_lshl_add_u64 v[218:219], v[224:225], 0, s[76:77]
	s_mov_b32 m0, s45
	s_nop 0
	global_load_lds_dwordx4 v[218:219], off
	s_waitcnt vmcnt(8)
	s_waitcnt lgkmcnt(0)
	s_barrier
	s_setprio 1
	v_mfma_f32_16x16x32_bf16 v[60:63], v[128:131], v[176:179], v[60:63]
	v_mfma_f32_16x16x32_bf16 v[56:59], v[136:139], v[176:179], v[56:59]
	v_mfma_f32_16x16x32_bf16 v[48:51], v[128:131], v[184:187], v[48:51]
	v_mfma_f32_16x16x32_bf16 v[40:43], v[136:139], v[184:187], v[40:43]
	v_mfma_f32_16x16x32_bf16 v[32:35], v[128:131], v[194:197], v[32:35]
	v_mfma_f32_16x16x32_bf16 v[24:27], v[136:139], v[194:197], v[24:27]
	v_mfma_f32_16x16x32_bf16 v[16:19], v[128:131], v[202:205], v[16:19]
	v_mfma_f32_16x16x32_bf16 v[8:11], v[136:139], v[202:205], v[8:11]
	v_mfma_f32_16x16x32_bf16 v[60:63], v[132:135], v[180:183], v[60:63]
	v_mfma_f32_16x16x32_bf16 v[56:59], v[140:143], v[180:183], v[56:59]
	v_mfma_f32_16x16x32_bf16 v[48:51], v[132:135], v[188:191], v[48:51]
	v_mfma_f32_16x16x32_bf16 v[40:43], v[140:143], v[188:191], v[40:43]
	v_mfma_f32_16x16x32_bf16 v[32:35], v[132:135], v[198:201], v[32:35]
	v_mfma_f32_16x16x32_bf16 v[24:27], v[140:143], v[198:201], v[24:27]
	v_mfma_f32_16x16x32_bf16 v[16:19], v[132:135], v[214:217], v[16:19]
	v_mfma_f32_16x16x32_bf16 v[8:11], v[140:143], v[214:217], v[8:11]
	v_mfma_f32_16x16x32_bf16 v[52:55], v[144:147], v[176:179], v[52:55]
	v_mfma_f32_16x16x32_bf16 v[44:47], v[152:155], v[176:179], v[44:47]
	v_mfma_f32_16x16x32_bf16 v[36:39], v[144:147], v[184:187], v[36:39]
	v_mfma_f32_16x16x32_bf16 v[28:31], v[152:155], v[184:187], v[28:31]
	v_mfma_f32_16x16x32_bf16 v[20:23], v[144:147], v[194:197], v[20:23]
	v_mfma_f32_16x16x32_bf16 v[12:15], v[152:155], v[194:197], v[12:15]
	v_mfma_f32_16x16x32_bf16 v[4:7], v[144:147], v[202:205], v[4:7]
	v_mfma_f32_16x16x32_bf16 v[0:3], v[152:155], v[202:205], v[0:3]
	v_mfma_f32_16x16x32_bf16 v[52:55], v[148:151], v[180:183], v[52:55]
	v_mfma_f32_16x16x32_bf16 v[44:47], v[172:175], v[180:183], v[44:47]
	v_mfma_f32_16x16x32_bf16 v[36:39], v[148:151], v[188:191], v[36:39]
	v_mfma_f32_16x16x32_bf16 v[28:31], v[172:175], v[188:191], v[28:31]
	v_mfma_f32_16x16x32_bf16 v[20:23], v[148:151], v[198:201], v[20:23]
	v_mfma_f32_16x16x32_bf16 v[12:15], v[172:175], v[198:201], v[12:15]
	v_mfma_f32_16x16x32_bf16 v[4:7], v[148:151], v[214:217], v[4:7]
	v_mfma_f32_16x16x32_bf16 v[0:3], v[172:175], v[214:217], v[0:3]
	s_setprio 0
	s_barrier
	s_add_i32 s13, s13, 2
	s_add_u32 s9, s9, 0x100
	s_addc_u32 s11, s11, 0
	s_add_u32 s24, s24, 0x100
	s_addc_u32 s25, s25, 0
	s_cmpk_gt_u32 s13, 0x7d
	s_cbranch_scc0 .LBB0_670
	s_and_b64 vcc, exec, s[4:5]
	s_cbranch_vccz .LBB0_673
	s_barrier

.LBB0_917:
	v_or_b32_e32 v192, s1, v94
	v_lshlrev_b64 v[0:1], 15, v[192:193]
	v_lshl_add_u64 v[0:1], v[84:85], 0, v[0:1]
	ds_read_b128 v[2:5], v93 offset:2048
	ds_read_b128 v[6:9], v93 offset:2064
	global_load_dwordx4 v[10:13], v[0:1], off
	global_load_dwordx4 v[140:143], v[0:1], off offset:32
	global_load_dwordx4 v[144:147], v[0:1], off offset:64
	global_load_dwordx4 v[148:151], v[0:1], off offset:96
	global_load_dwordx4 v[152:155], v[0:1], off offset:128
	global_load_dwordx4 v[156:159], v[0:1], off offset:160
	global_load_dwordx4 v[160:163], v[0:1], off offset:192
	global_load_dwordx4 v[164:167], v[0:1], off offset:224
	s_xor_b64 s[48:49], s[48:49], -1
	v_add_u32_e32 v115, s1, v95
	v_add_u32_e32 v116, s1, v96
	v_add_u32_e32 v117, s1, v97
	v_add_u32_e32 v118, s1, v98
	v_add_u32_e32 v119, s1, v99
	v_add_u32_e32 v120, s1, v100
	v_add_u32_e32 v121, s1, v101
	v_add_u32_e32 v122, s1, v102
	v_add_u32_e32 v123, s1, v103
	v_add_u32_e32 v124, s1, v104
	v_add_u32_e32 v125, s1, v105
	v_add_u32_e32 v126, s1, v106
	v_add_u32_e32 v127, s1, v107
	v_add_u32_e32 v128, s1, v108
	v_add_u32_e32 v129, s1, v109
	v_add_u32_e32 v130, s1, v110
	v_add_u32_e32 v131, s1, v111
	s_mov_b64 s[50:51], 0
	v_mov_b32_e32 v88, v113
	s_waitcnt vmcnt(0) lgkmcnt(0)
	v_lshlrev_b32_e32 v14, 16, v10
	v_and_b32_e32 v15, 0xffff0000, v10
	v_pk_mul_f32 v[2:3], v[2:3], v[14:15]
	s_nop 0
	v_cvt_pk_bf16_f32 v16, v2, v3
	v_lshlrev_b32_e32 v2, 16, v11
	v_and_b32_e32 v3, 0xffff0000, v11
	v_pk_mul_f32 v[2:3], v[4:5], v[2:3]
	s_nop 0
	v_cvt_pk_bf16_f32 v17, v2, v3
	v_lshlrev_b32_e32 v2, 16, v12
	v_and_b32_e32 v3, 0xffff0000, v12
	v_pk_mul_f32 v[2:3], v[6:7], v[2:3]
	s_nop 0
	v_cvt_pk_bf16_f32 v18, v2, v3
	v_lshlrev_b32_e32 v2, 16, v13
	v_and_b32_e32 v3, 0xffff0000, v13
	v_pk_mul_f32 v[2:3], v[8:9], v[2:3]
	s_nop 0
	v_cvt_pk_bf16_f32 v19, v2, v3
	ds_read_b128 v[2:5], v93 offset:2112
	ds_read_b128 v[6:9], v93 offset:2128
	s_waitcnt lgkmcnt(0)
	v_lshlrev_b32_e32 v14, 16, v140
	v_and_b32_e32 v15, 0xffff0000, v140
	v_pk_mul_f32 v[2:3], v[2:3], v[14:15]
	s_nop 0
	v_cvt_pk_bf16_f32 v20, v2, v3
	v_lshlrev_b32_e32 v2, 16, v141
	v_and_b32_e32 v3, 0xffff0000, v141
	v_pk_mul_f32 v[2:3], v[4:5], v[2:3]
	s_nop 0
	v_cvt_pk_bf16_f32 v21, v2, v3
	v_lshlrev_b32_e32 v2, 16, v142
	v_and_b32_e32 v3, 0xffff0000, v142
	v_pk_mul_f32 v[2:3], v[6:7], v[2:3]
	s_nop 0
	v_cvt_pk_bf16_f32 v22, v2, v3
	v_lshlrev_b32_e32 v2, 16, v143
	v_and_b32_e32 v3, 0xffff0000, v143
	v_pk_mul_f32 v[2:3], v[8:9], v[2:3]
	s_nop 0
	v_cvt_pk_bf16_f32 v23, v2, v3
	ds_read_b128 v[2:5], v93 offset:2176
	ds_read_b128 v[6:9], v93 offset:2192
	s_waitcnt lgkmcnt(0)
	v_lshlrev_b32_e32 v14, 16, v144
	v_and_b32_e32 v15, 0xffff0000, v144
	v_pk_mul_f32 v[2:3], v[2:3], v[14:15]
	s_nop 0
	v_cvt_pk_bf16_f32 v24, v2, v3
	v_lshlrev_b32_e32 v2, 16, v145
	v_and_b32_e32 v3, 0xffff0000, v145
	v_pk_mul_f32 v[2:3], v[4:5], v[2:3]
	s_nop 0
	v_cvt_pk_bf16_f32 v25, v2, v3
	v_lshlrev_b32_e32 v2, 16, v146
	v_and_b32_e32 v3, 0xffff0000, v146
	v_pk_mul_f32 v[2:3], v[6:7], v[2:3]
	s_nop 0
	v_cvt_pk_bf16_f32 v26, v2, v3
	v_lshlrev_b32_e32 v2, 16, v147
	v_and_b32_e32 v3, 0xffff0000, v147
	v_pk_mul_f32 v[2:3], v[8:9], v[2:3]
	s_nop 0
	v_cvt_pk_bf16_f32 v27, v2, v3
	ds_read_b128 v[2:5], v93 offset:2240
	ds_read_b128 v[6:9], v93 offset:2256
	s_waitcnt lgkmcnt(0)
	v_lshlrev_b32_e32 v14, 16, v148
	v_and_b32_e32 v15, 0xffff0000, v148
	v_pk_mul_f32 v[2:3], v[2:3], v[14:15]
	s_nop 0
	v_cvt_pk_bf16_f32 v28, v2, v3
	v_lshlrev_b32_e32 v2, 16, v149
	v_and_b32_e32 v3, 0xffff0000, v149
	v_pk_mul_f32 v[2:3], v[4:5], v[2:3]
	s_nop 0
	v_cvt_pk_bf16_f32 v29, v2, v3
	v_lshlrev_b32_e32 v2, 16, v150
	v_and_b32_e32 v3, 0xffff0000, v150
	v_pk_mul_f32 v[2:3], v[6:7], v[2:3]
	s_nop 0
	v_cvt_pk_bf16_f32 v30, v2, v3
	v_lshlrev_b32_e32 v2, 16, v151
	v_and_b32_e32 v3, 0xffff0000, v151
	v_pk_mul_f32 v[2:3], v[8:9], v[2:3]
	s_nop 0
	v_cvt_pk_bf16_f32 v31, v2, v3
	ds_read_b128 v[2:5], v93 offset:2304
	ds_read_b128 v[6:9], v93 offset:2320
	s_waitcnt lgkmcnt(0)
	v_lshlrev_b32_e32 v14, 16, v152
	v_and_b32_e32 v15, 0xffff0000, v152
	v_pk_mul_f32 v[2:3], v[2:3], v[14:15]
	s_nop 0
	v_cvt_pk_bf16_f32 v32, v2, v3
	v_lshlrev_b32_e32 v2, 16, v153
	v_and_b32_e32 v3, 0xffff0000, v153
	v_pk_mul_f32 v[2:3], v[4:5], v[2:3]
	s_nop 0
	v_cvt_pk_bf16_f32 v33, v2, v3
	v_lshlrev_b32_e32 v2, 16, v154
	v_and_b32_e32 v3, 0xffff0000, v154
	v_pk_mul_f32 v[2:3], v[6:7], v[2:3]
	s_nop 0
	v_cvt_pk_bf16_f32 v34, v2, v3
	v_lshlrev_b32_e32 v2, 16, v155
	v_and_b32_e32 v3, 0xffff0000, v155
	v_pk_mul_f32 v[2:3], v[8:9], v[2:3]
	s_nop 0
	v_cvt_pk_bf16_f32 v35, v2, v3
	ds_read_b128 v[2:5], v93 offset:2368
	ds_read_b128 v[6:9], v93 offset:2384
	s_waitcnt lgkmcnt(0)
	v_lshlrev_b32_e32 v14, 16, v156
	v_and_b32_e32 v15, 0xffff0000, v156
	v_pk_mul_f32 v[2:3], v[2:3], v[14:15]
	s_nop 0
	v_cvt_pk_bf16_f32 v36, v2, v3
	v_lshlrev_b32_e32 v2, 16, v157
	v_and_b32_e32 v3, 0xffff0000, v157
	v_pk_mul_f32 v[2:3], v[4:5], v[2:3]
	s_nop 0
	v_cvt_pk_bf16_f32 v37, v2, v3
	v_lshlrev_b32_e32 v2, 16, v158
	v_and_b32_e32 v3, 0xffff0000, v158
	v_pk_mul_f32 v[2:3], v[6:7], v[2:3]
	s_nop 0
	v_cvt_pk_bf16_f32 v38, v2, v3
	v_lshlrev_b32_e32 v2, 16, v159
	v_and_b32_e32 v3, 0xffff0000, v159
	v_pk_mul_f32 v[2:3], v[8:9], v[2:3]
	s_nop 0
	v_cvt_pk_bf16_f32 v39, v2, v3
	ds_read_b128 v[2:5], v93 offset:2432
	ds_read_b128 v[6:9], v93 offset:2448
	s_waitcnt lgkmcnt(0)
	v_lshlrev_b32_e32 v14, 16, v160
	v_and_b32_e32 v15, 0xffff0000, v160
	v_pk_mul_f32 v[2:3], v[2:3], v[14:15]
	s_nop 0
	v_cvt_pk_bf16_f32 v40, v2, v3
	v_lshlrev_b32_e32 v2, 16, v161
	v_and_b32_e32 v3, 0xffff0000, v161
	v_pk_mul_f32 v[2:3], v[4:5], v[2:3]
	s_nop 0
	v_cvt_pk_bf16_f32 v41, v2, v3
	v_lshlrev_b32_e32 v2, 16, v162
	v_and_b32_e32 v3, 0xffff0000, v162
	v_pk_mul_f32 v[2:3], v[6:7], v[2:3]
	s_nop 0
	v_cvt_pk_bf16_f32 v42, v2, v3
	v_lshlrev_b32_e32 v2, 16, v163
	v_and_b32_e32 v3, 0xffff0000, v163
	v_pk_mul_f32 v[2:3], v[8:9], v[2:3]
	s_nop 0
	v_cvt_pk_bf16_f32 v43, v2, v3
	ds_read_b128 v[2:5], v93 offset:2496
	ds_read_b128 v[6:9], v93 offset:2512
	s_waitcnt lgkmcnt(0)
	v_lshlrev_b32_e32 v0, 16, v164
	v_and_b32_e32 v1, 0xffff0000, v164
	v_pk_mul_f32 v[0:1], v[2:3], v[0:1]
	s_nop 0
	v_cvt_pk_bf16_f32 v44, v0, v1
	v_lshlrev_b32_e32 v0, 16, v165
	v_and_b32_e32 v1, 0xffff0000, v165
	v_pk_mul_f32 v[0:1], v[4:5], v[0:1]
	s_nop 0
	v_cvt_pk_bf16_f32 v45, v0, v1
	v_lshlrev_b32_e32 v0, 16, v166
	v_and_b32_e32 v1, 0xffff0000, v166
	v_pk_mul_f32 v[0:1], v[6:7], v[0:1]
	s_nop 0
	v_cvt_pk_bf16_f32 v46, v0, v1
	v_lshlrev_b32_e32 v0, 16, v167
	v_and_b32_e32 v1, 0xffff0000, v167
	v_pk_mul_f32 v[0:1], v[8:9], v[0:1]
	s_nop 0
	v_cvt_pk_bf16_f32 v47, v0, v1
	v_lshl_add_u64 v[0:1], v[192:193], 2, s[4:5]
	global_load_dword v114, v[0:1], off

.LBB0_1021:
	s_add_i32 s64, s63, 2
	s_add_u32 s14, s12, 0x100
	s_addc_u32 s15, s13, 0
	s_add_i32 s65, 0, 0x10000
	s_cmp_eq_u32 s63, 38
	s_cselect_b32 s19, s9, s15
	s_cselect_b32 s18, s8, s14
	s_cselect_b32 s17, s11, s61
	s_cselect_b32 s16, s10, s60
	s_add_i32 s66, 0, 0x14000
	v_add_u32_e32 v140, s65, v222
	v_add_u32_e32 v156, s66, v222
	ds_read_b128 v[128:131], v140
	ds_read_b128 v[132:135], v140 offset:1024
	ds_read_b128 v[136:139], v140 offset:2048
	ds_read_b128 v[140:143], v140 offset:3072
	ds_read_b128 v[144:147], v156
	ds_read_b128 v[148:151], v156 offset:1024
	ds_read_b128 v[152:155], v156 offset:2048
	ds_read_b128 v[156:159], v156 offset:3072
	v_lshl_add_u64 v[228:229], s[12:13], 0, v[204:205]
	s_add_i32 m0, s26, 0xc000
	ds_read_b128 v[160:163], v225
	ds_read_b128 v[164:167], v225 offset:1024
	ds_read_b128 v[168:171], v225 offset:2048
	ds_read_b128 v[172:175], v225 offset:3072
	ds_read_b128 v[176:179], v225 offset:4096
	ds_read_b128 v[180:183], v225 offset:5120
	ds_read_b128 v[184:187], v225 offset:6144
	ds_read_b128 v[188:191], v225 offset:7168
	global_load_lds_dwordx4 v[228:229], off
	v_lshl_add_u64 v[228:229], s[12:13], 0, v[202:203]
	s_add_i32 m0, s26, 0xe000
	s_nop 0
	global_load_lds_dwordx4 v[228:229], off
	s_waitcnt vmcnt(8)
	s_waitcnt lgkmcnt(0)
	s_barrier
	s_setprio 1
	v_mfma_f32_16x16x32_bf16 v[124:127], v[128:131], v[160:163], v[124:127]
	v_mfma_f32_16x16x32_bf16 v[120:123], v[136:139], v[160:163], v[120:123]
	v_mfma_f32_16x16x32_bf16 v[108:111], v[128:131], v[168:171], v[108:111]
	v_mfma_f32_16x16x32_bf16 v[104:107], v[136:139], v[168:171], v[104:107]
	v_mfma_f32_16x16x32_bf16 v[92:95], v[128:131], v[176:179], v[92:95]
	v_mfma_f32_16x16x32_bf16 v[88:91], v[136:139], v[176:179], v[88:91]
	v_mfma_f32_16x16x32_bf16 v[76:79], v[128:131], v[184:187], v[76:79]
	v_mfma_f32_16x16x32_bf16 v[72:75], v[136:139], v[184:187], v[72:75]
	v_mfma_f32_16x16x32_bf16 v[124:127], v[132:135], v[164:167], v[124:127]
	v_mfma_f32_16x16x32_bf16 v[120:123], v[140:143], v[164:167], v[120:123]
	v_mfma_f32_16x16x32_bf16 v[108:111], v[132:135], v[172:175], v[108:111]
	v_mfma_f32_16x16x32_bf16 v[104:107], v[140:143], v[172:175], v[104:107]
	v_mfma_f32_16x16x32_bf16 v[92:95], v[132:135], v[180:183], v[92:95]
	v_mfma_f32_16x16x32_bf16 v[88:91], v[140:143], v[180:183], v[88:91]
	v_mfma_f32_16x16x32_bf16 v[76:79], v[132:135], v[188:191], v[76:79]
	v_mfma_f32_16x16x32_bf16 v[72:75], v[140:143], v[188:191], v[72:75]
	v_mfma_f32_16x16x32_bf16 v[116:119], v[144:147], v[160:163], v[116:119]
	v_mfma_f32_16x16x32_bf16 v[112:115], v[152:155], v[160:163], v[112:115]
	v_mfma_f32_16x16x32_bf16 v[100:103], v[144:147], v[168:171], v[100:103]
	v_mfma_f32_16x16x32_bf16 v[96:99], v[152:155], v[168:171], v[96:99]
	v_mfma_f32_16x16x32_bf16 v[84:87], v[144:147], v[176:179], v[84:87]
	v_mfma_f32_16x16x32_bf16 v[80:83], v[152:155], v[176:179], v[80:83]
	v_mfma_f32_16x16x32_bf16 v[68:71], v[144:147], v[184:187], v[68:71]
	v_mfma_f32_16x16x32_bf16 v[64:67], v[152:155], v[184:187], v[64:67]
	v_mfma_f32_16x16x32_bf16 v[116:119], v[148:151], v[164:167], v[116:119]
	v_mfma_f32_16x16x32_bf16 v[112:115], v[156:159], v[164:167], v[112:115]
	v_mfma_f32_16x16x32_bf16 v[100:103], v[148:151], v[172:175], v[100:103]
	v_mfma_f32_16x16x32_bf16 v[96:99], v[156:159], v[172:175], v[96:99]
	v_mfma_f32_16x16x32_bf16 v[84:87], v[148:151], v[180:183], v[84:87]
	v_mfma_f32_16x16x32_bf16 v[80:83], v[156:159], v[180:183], v[80:83]
	v_mfma_f32_16x16x32_bf16 v[68:71], v[148:151], v[188:191], v[68:71]
	v_mfma_f32_16x16x32_bf16 v[64:67], v[156:159], v[188:191], v[64:67]
	s_setprio 0
	s_barrier
	s_add_i32 s12, s65, s25
	v_lshl_add_u64 v[228:229], s[16:17], 0, v[196:197]
	s_mov_b32 m0, s12
	ds_read_b128 v[160:163], v225 offset:16384
	ds_read_b128 v[164:167], v225 offset:17408
	ds_read_b128 v[168:171], v225 offset:18432
	ds_read_b128 v[172:175], v225 offset:19456
	ds_read_b128 v[176:179], v225 offset:20480
	ds_read_b128 v[180:183], v225 offset:21504
	ds_read_b128 v[184:187], v225 offset:22528
	ds_read_b128 v[188:191], v225 offset:23552
	global_load_lds_dwordx4 v[228:229], off
	s_add_i32 m0, s12, 0x2000
	s_add_u32 s12, s16, 0xa0000
	v_lshl_add_u64 v[230:231], s[16:17], 0, v[200:201]
	s_addc_u32 s13, s17, 0
	s_add_i32 s65, s66, s25
	global_load_lds_dwordx4 v[230:231], off
	v_lshl_add_u64 v[232:233], s[12:13], 0, v[196:197]
	s_mov_b32 m0, s65
	v_lshl_add_u64 v[234:235], s[18:19], 0, v[198:199]
	global_load_lds_dwordx4 v[232:233], off
	v_lshl_add_u64 v[232:233], s[12:13], 0, v[200:201]
	s_add_i32 m0, s65, 0x2000
	s_nop 0
	global_load_lds_dwordx4 v[232:233], off
	v_lshl_add_u64 v[232:233], s[18:19], 0, v[194:195]
	s_mov_b32 m0, s26
	s_nop 0
	global_load_lds_dwordx4 v[232:233], off
	s_mov_b32 m0, s27
	s_nop 0
	global_load_lds_dwordx4 v[234:235], off
	s_waitcnt vmcnt(8)
	s_waitcnt lgkmcnt(0)
	s_barrier
	s_setprio 1
	v_mfma_f32_16x16x32_bf16 v[60:63], v[128:131], v[160:163], v[60:63]
	v_mfma_f32_16x16x32_bf16 v[56:59], v[136:139], v[160:163], v[56:59]
	v_mfma_f32_16x16x32_bf16 v[44:47], v[128:131], v[168:171], v[44:47]
	v_mfma_f32_16x16x32_bf16 v[40:43], v[136:139], v[168:171], v[40:43]
	v_mfma_f32_16x16x32_bf16 v[28:31], v[128:131], v[176:179], v[28:31]
	v_mfma_f32_16x16x32_bf16 v[24:27], v[136:139], v[176:179], v[24:27]
	v_mfma_f32_16x16x32_bf16 v[12:15], v[128:131], v[184:187], v[12:15]
	v_mfma_f32_16x16x32_bf16 v[8:11], v[136:139], v[184:187], v[8:11]
	v_mfma_f32_16x16x32_bf16 v[60:63], v[132:135], v[164:167], v[60:63]
	v_mfma_f32_16x16x32_bf16 v[56:59], v[140:143], v[164:167], v[56:59]
	v_mfma_f32_16x16x32_bf16 v[44:47], v[132:135], v[172:175], v[44:47]
	v_mfma_f32_16x16x32_bf16 v[40:43], v[140:143], v[172:175], v[40:43]
	v_mfma_f32_16x16x32_bf16 v[28:31], v[132:135], v[180:183], v[28:31]
	v_mfma_f32_16x16x32_bf16 v[24:27], v[140:143], v[180:183], v[24:27]
	v_mfma_f32_16x16x32_bf16 v[12:15], v[132:135], v[188:191], v[12:15]
	v_mfma_f32_16x16x32_bf16 v[8:11], v[140:143], v[188:191], v[8:11]
	v_mfma_f32_16x16x32_bf16 v[52:55], v[144:147], v[160:163], v[52:55]
	v_mfma_f32_16x16x32_bf16 v[48:51], v[152:155], v[160:163], v[48:51]
	v_mfma_f32_16x16x32_bf16 v[36:39], v[144:147], v[168:171], v[36:39]
	v_mfma_f32_16x16x32_bf16 v[32:35], v[152:155], v[168:171], v[32:35]
	v_mfma_f32_16x16x32_bf16 v[20:23], v[144:147], v[176:179], v[20:23]
	v_mfma_f32_16x16x32_bf16 v[16:19], v[152:155], v[176:179], v[16:19]
	v_mfma_f32_16x16x32_bf16 v[4:7], v[144:147], v[184:187], v[4:7]
	v_mfma_f32_16x16x32_bf16 v[0:3], v[152:155], v[184:187], v[0:3]
	v_mfma_f32_16x16x32_bf16 v[52:55], v[148:151], v[164:167], v[52:55]
	v_mfma_f32_16x16x32_bf16 v[48:51], v[156:159], v[164:167], v[48:51]
	v_mfma_f32_16x16x32_bf16 v[36:39], v[148:151], v[172:175], v[36:39]
	v_mfma_f32_16x16x32_bf16 v[32:35], v[156:159], v[172:175], v[32:35]
	v_mfma_f32_16x16x32_bf16 v[20:23], v[148:151], v[180:183], v[20:23]
	v_mfma_f32_16x16x32_bf16 v[16:19], v[156:159], v[180:183], v[16:19]
	v_mfma_f32_16x16x32_bf16 v[4:7], v[148:151], v[188:191], v[4:7]
	v_mfma_f32_16x16x32_bf16 v[0:3], v[156:159], v[188:191], v[0:3]
	s_setprio 0
	s_barrier
	s_add_i32 s65, 0, 0x18000
	s_add_i32 s66, 0, 0x1c000
	v_add_u32_e32 v140, s65, v222
	v_add_u32_e32 v156, s66, v222
	ds_read_b128 v[128:131], v140
	ds_read_b128 v[132:135], v140 offset:1024
	ds_read_b128 v[136:139], v140 offset:2048
	ds_read_b128 v[140:143], v140 offset:3072
	ds_read_b128 v[144:147], v156
	ds_read_b128 v[148:151], v156 offset:1024
	ds_read_b128 v[152:155], v156 offset:2048
	ds_read_b128 v[156:159], v156 offset:3072
	s_add_u32 s12, s18, 0xa0000
	s_addc_u32 s13, s19, 0
	s_mov_b32 m0, s28
	v_lshl_add_u64 v[236:237], s[12:13], 0, v[194:195]
	ds_read_b128 v[160:163], v225 offset:32768
	ds_read_b128 v[164:167], v225 offset:33792
	ds_read_b128 v[168:171], v225 offset:34816
	ds_read_b128 v[172:175], v225 offset:35840
	ds_read_b128 v[176:179], v225 offset:36864
	ds_read_b128 v[180:183], v225 offset:37888
	ds_read_b128 v[184:187], v225 offset:38912
	ds_read_b128 v[188:191], v225 offset:39936
	global_load_lds_dwordx4 v[236:237], off
	v_lshl_add_u64 v[236:237], s[12:13], 0, v[198:199]
	s_mov_b32 m0, s29
	s_nop 0
	global_load_lds_dwordx4 v[236:237], off
	s_waitcnt vmcnt(8)
	s_waitcnt lgkmcnt(0)
	s_barrier
	s_setprio 1
	v_mfma_f32_16x16x32_bf16 v[124:127], v[128:131], v[160:163], v[124:127]
	v_mfma_f32_16x16x32_bf16 v[120:123], v[136:139], v[160:163], v[120:123]
	v_mfma_f32_16x16x32_bf16 v[108:111], v[128:131], v[168:171], v[108:111]
	v_mfma_f32_16x16x32_bf16 v[104:107], v[136:139], v[168:171], v[104:107]
	v_mfma_f32_16x16x32_bf16 v[92:95], v[128:131], v[176:179], v[92:95]
	v_mfma_f32_16x16x32_bf16 v[88:91], v[136:139], v[176:179], v[88:91]
	v_mfma_f32_16x16x32_bf16 v[76:79], v[128:131], v[184:187], v[76:79]
	v_mfma_f32_16x16x32_bf16 v[72:75], v[136:139], v[184:187], v[72:75]
	v_mfma_f32_16x16x32_bf16 v[124:127], v[132:135], v[164:167], v[124:127]
	v_mfma_f32_16x16x32_bf16 v[120:123], v[140:143], v[164:167], v[120:123]
	v_mfma_f32_16x16x32_bf16 v[108:111], v[132:135], v[172:175], v[108:111]
	v_mfma_f32_16x16x32_bf16 v[104:107], v[140:143], v[172:175], v[104:107]
	v_mfma_f32_16x16x32_bf16 v[92:95], v[132:135], v[180:183], v[92:95]
	v_mfma_f32_16x16x32_bf16 v[88:91], v[140:143], v[180:183], v[88:91]
	v_mfma_f32_16x16x32_bf16 v[76:79], v[132:135], v[188:191], v[76:79]
	v_mfma_f32_16x16x32_bf16 v[72:75], v[140:143], v[188:191], v[72:75]
	v_mfma_f32_16x16x32_bf16 v[116:119], v[144:147], v[160:163], v[116:119]
	v_mfma_f32_16x16x32_bf16 v[112:115], v[152:155], v[160:163], v[112:115]
	v_mfma_f32_16x16x32_bf16 v[100:103], v[144:147], v[168:171], v[100:103]
	v_mfma_f32_16x16x32_bf16 v[96:99], v[152:155], v[168:171], v[96:99]
	v_mfma_f32_16x16x32_bf16 v[84:87], v[144:147], v[176:179], v[84:87]
	v_mfma_f32_16x16x32_bf16 v[80:83], v[152:155], v[176:179], v[80:83]
	v_mfma_f32_16x16x32_bf16 v[68:71], v[144:147], v[184:187], v[68:71]
	v_mfma_f32_16x16x32_bf16 v[64:67], v[152:155], v[184:187], v[64:67]
	v_mfma_f32_16x16x32_bf16 v[116:119], v[148:151], v[164:167], v[116:119]
	v_mfma_f32_16x16x32_bf16 v[112:115], v[156:159], v[164:167], v[112:115]
	v_mfma_f32_16x16x32_bf16 v[100:103], v[148:151], v[172:175], v[100:103]
	v_mfma_f32_16x16x32_bf16 v[96:99], v[156:159], v[172:175], v[96:99]
	v_mfma_f32_16x16x32_bf16 v[84:87], v[148:151], v[180:183], v[84:87]
	v_mfma_f32_16x16x32_bf16 v[80:83], v[156:159], v[180:183], v[80:83]
	v_mfma_f32_16x16x32_bf16 v[68:71], v[148:151], v[188:191], v[68:71]
	v_mfma_f32_16x16x32_bf16 v[64:67], v[156:159], v[188:191], v[64:67]
	s_setprio 0
	s_barrier
	s_add_i32 s12, s65, s25
	v_lshl_add_u64 v[228:229], v[228:229], 0, s[76:77]
	s_mov_b32 m0, s12
	ds_read_b128 v[160:163], v225 offset:49152
	ds_read_b128 v[164:167], v225 offset:50176
	ds_read_b128 v[168:171], v225 offset:51200
	ds_read_b128 v[172:175], v225 offset:52224
	ds_read_b128 v[176:179], v225 offset:53248
	ds_read_b128 v[180:183], v225 offset:54272
	ds_read_b128 v[184:187], v225 offset:55296
	ds_read_b128 v[188:191], v225 offset:56320
	global_load_lds_dwordx4 v[228:229], off
	s_add_i32 m0, s12, 0x2000
	s_add_u32 s12, s16, 0xa0080
	v_lshl_add_u64 v[228:229], v[230:231], 0, s[76:77]
	s_addc_u32 s13, s17, 0
	s_add_i32 s16, s66, s25
	global_load_lds_dwordx4 v[228:229], off
	v_lshl_add_u64 v[228:229], s[12:13], 0, v[196:197]
	s_mov_b32 m0, s16
	s_nop 0
	global_load_lds_dwordx4 v[228:229], off
	v_lshl_add_u64 v[228:229], s[12:13], 0, v[200:201]
	s_add_i32 m0, s16, 0x2000
	s_nop 0
	global_load_lds_dwordx4 v[228:229], off
	v_lshl_add_u64 v[228:229], v[232:233], 0, s[76:77]
	s_mov_b32 m0, s36
	s_nop 0
	global_load_lds_dwordx4 v[228:229], off
	v_lshl_add_u64 v[228:229], v[234:235], 0, s[76:77]
	s_mov_b32 m0, s37
	s_nop 0
	global_load_lds_dwordx4 v[228:229], off
	s_waitcnt vmcnt(8)
	s_waitcnt lgkmcnt(0)
	s_barrier
	s_setprio 1
	v_mfma_f32_16x16x32_bf16 v[60:63], v[128:131], v[160:163], v[60:63]
	v_mfma_f32_16x16x32_bf16 v[56:59], v[136:139], v[160:163], v[56:59]
	v_mfma_f32_16x16x32_bf16 v[44:47], v[128:131], v[168:171], v[44:47]
	v_mfma_f32_16x16x32_bf16 v[40:43], v[136:139], v[168:171], v[40:43]
	v_mfma_f32_16x16x32_bf16 v[28:31], v[128:131], v[176:179], v[28:31]
	v_mfma_f32_16x16x32_bf16 v[24:27], v[136:139], v[176:179], v[24:27]
	v_mfma_f32_16x16x32_bf16 v[12:15], v[128:131], v[184:187], v[12:15]
	v_mfma_f32_16x16x32_bf16 v[8:11], v[136:139], v[184:187], v[8:11]
	v_mfma_f32_16x16x32_bf16 v[60:63], v[132:135], v[164:167], v[60:63]
	v_mfma_f32_16x16x32_bf16 v[56:59], v[140:143], v[164:167], v[56:59]
	v_mfma_f32_16x16x32_bf16 v[44:47], v[132:135], v[172:175], v[44:47]
	v_mfma_f32_16x16x32_bf16 v[40:43], v[140:143], v[172:175], v[40:43]
	v_mfma_f32_16x16x32_bf16 v[28:31], v[132:135], v[180:183], v[28:31]
	v_mfma_f32_16x16x32_bf16 v[24:27], v[140:143], v[180:183], v[24:27]
	v_mfma_f32_16x16x32_bf16 v[12:15], v[132:135], v[188:191], v[12:15]
	v_mfma_f32_16x16x32_bf16 v[8:11], v[140:143], v[188:191], v[8:11]
	v_mfma_f32_16x16x32_bf16 v[52:55], v[144:147], v[160:163], v[52:55]
	v_mfma_f32_16x16x32_bf16 v[48:51], v[152:155], v[160:163], v[48:51]
	v_mfma_f32_16x16x32_bf16 v[36:39], v[144:147], v[168:171], v[36:39]
	v_mfma_f32_16x16x32_bf16 v[32:35], v[152:155], v[168:171], v[32:35]
	v_mfma_f32_16x16x32_bf16 v[20:23], v[144:147], v[176:179], v[20:23]
	v_mfma_f32_16x16x32_bf16 v[16:19], v[152:155], v[176:179], v[16:19]
	v_mfma_f32_16x16x32_bf16 v[4:7], v[144:147], v[184:187], v[4:7]
	v_mfma_f32_16x16x32_bf16 v[0:3], v[152:155], v[184:187], v[0:3]
	v_mfma_f32_16x16x32_bf16 v[52:55], v[148:151], v[164:167], v[52:55]
	v_mfma_f32_16x16x32_bf16 v[48:51], v[156:159], v[164:167], v[48:51]
	v_mfma_f32_16x16x32_bf16 v[36:39], v[148:151], v[172:175], v[36:39]
	v_mfma_f32_16x16x32_bf16 v[32:35], v[156:159], v[172:175], v[32:35]
	v_mfma_f32_16x16x32_bf16 v[20:23], v[148:151], v[180:183], v[20:23]
	v_mfma_f32_16x16x32_bf16 v[16:19], v[156:159], v[180:183], v[16:19]
	v_mfma_f32_16x16x32_bf16 v[4:7], v[148:151], v[188:191], v[4:7]
	v_mfma_f32_16x16x32_bf16 v[0:3], v[156:159], v[188:191], v[0:3]
	s_setprio 0
	s_barrier
	s_add_u32 s60, s60, 0x100
	s_addc_u32 s61, s61, 0
	s_add_i32 s62, s62, 1
	s_cmp_gt_u32 s63, 37
	s_mov_b64 s[12:13], s[14:15]
	s_mov_b32 s63, s64
	s_cbranch_scc1 .LBB0_1032

.LBB0_1099:
	s_add_u32 s18, s16, 0xfffc0080
	s_addc_u32 s19, s17, -1
	s_add_i32 s46, 0, 0x10000
	s_cmp_eq_u32 s45, 12
	s_cselect_b32 s21, s5, s19
	s_cselect_b32 s20, s9, s18
	s_cselect_b32 s19, s11, s44
	s_cselect_b32 s18, s42, s43
	s_add_i32 s48, 0, 0x14000
	v_add_u32_e32 v154, s46, v140
	v_add_u32_e32 v170, s48, v140
	ds_read_b128 v[142:145], v154
	ds_read_b128 v[146:149], v154 offset:1024
	ds_read_b128 v[150:153], v154 offset:2048
	ds_read_b128 v[154:157], v154 offset:3072
	ds_read_b128 v[158:161], v170
	ds_read_b128 v[162:165], v170 offset:1024
	ds_read_b128 v[166:169], v170 offset:2048
	ds_read_b128 v[170:173], v170 offset:3072
	v_lshl_add_u64 v[190:191], s[16:17], 0, v[136:137]
	s_add_i32 m0, s28, 0xc000
	ds_read_b128 v[174:177], v141
	ds_read_b128 v[178:181], v141 offset:1024
	ds_read_b128 v[182:185], v141 offset:2048
	ds_read_b128 v[186:189], v141 offset:3072
	ds_read_b128 v[194:197], v141 offset:4096
	ds_read_b128 v[198:201], v141 offset:5120
	ds_read_b128 v[202:205], v141 offset:6144
	ds_read_b128 v[220:223], v141 offset:7168
	global_load_lds_dwordx4 v[190:191], off
	v_lshl_add_u64 v[190:191], s[16:17], 0, v[134:135]
	s_add_i32 m0, s28, 0xe000
	s_nop 0
	global_load_lds_dwordx4 v[190:191], off
	s_waitcnt vmcnt(8)
	s_waitcnt lgkmcnt(0)
	s_barrier
	s_setprio 1
	v_mfma_f32_16x16x32_bf16 v[124:127], v[142:145], v[174:177], v[124:127]
	v_mfma_f32_16x16x32_bf16 v[120:123], v[150:153], v[174:177], v[120:123]
	v_mfma_f32_16x16x32_bf16 v[116:119], v[142:145], v[182:185], v[116:119]
	v_mfma_f32_16x16x32_bf16 v[112:115], v[150:153], v[182:185], v[112:115]
	v_mfma_f32_16x16x32_bf16 v[100:103], v[142:145], v[194:197], v[100:103]
	v_mfma_f32_16x16x32_bf16 v[96:99], v[150:153], v[194:197], v[96:99]
	v_mfma_f32_16x16x32_bf16 v[84:87], v[142:145], v[202:205], v[84:87]
	v_mfma_f32_16x16x32_bf16 v[80:83], v[150:153], v[202:205], v[80:83]
	v_mfma_f32_16x16x32_bf16 v[124:127], v[146:149], v[178:181], v[124:127]
	v_mfma_f32_16x16x32_bf16 v[120:123], v[154:157], v[178:181], v[120:123]
	v_mfma_f32_16x16x32_bf16 v[116:119], v[146:149], v[186:189], v[116:119]
	v_mfma_f32_16x16x32_bf16 v[112:115], v[154:157], v[186:189], v[112:115]
	v_mfma_f32_16x16x32_bf16 v[100:103], v[146:149], v[198:201], v[100:103]
	v_mfma_f32_16x16x32_bf16 v[96:99], v[154:157], v[198:201], v[96:99]
	v_mfma_f32_16x16x32_bf16 v[84:87], v[146:149], v[220:223], v[84:87]
	v_mfma_f32_16x16x32_bf16 v[80:83], v[154:157], v[220:223], v[80:83]
	v_mfma_f32_16x16x32_bf16 v[108:111], v[158:161], v[174:177], v[108:111]
	v_mfma_f32_16x16x32_bf16 v[104:107], v[166:169], v[174:177], v[104:107]
	v_mfma_f32_16x16x32_bf16 v[92:95], v[158:161], v[182:185], v[92:95]
	v_mfma_f32_16x16x32_bf16 v[88:91], v[166:169], v[182:185], v[88:91]
	v_mfma_f32_16x16x32_bf16 v[76:79], v[158:161], v[194:197], v[76:79]
	v_mfma_f32_16x16x32_bf16 v[72:75], v[166:169], v[194:197], v[72:75]
	v_mfma_f32_16x16x32_bf16 v[68:71], v[158:161], v[202:205], v[68:71]
	v_mfma_f32_16x16x32_bf16 v[64:67], v[166:169], v[202:205], v[64:67]
	v_mfma_f32_16x16x32_bf16 v[108:111], v[162:165], v[178:181], v[108:111]
	v_mfma_f32_16x16x32_bf16 v[104:107], v[170:173], v[178:181], v[104:107]
	v_mfma_f32_16x16x32_bf16 v[92:95], v[162:165], v[186:189], v[92:95]
	v_mfma_f32_16x16x32_bf16 v[88:91], v[170:173], v[186:189], v[88:91]
	v_mfma_f32_16x16x32_bf16 v[76:79], v[162:165], v[198:201], v[76:79]
	v_mfma_f32_16x16x32_bf16 v[72:75], v[170:173], v[198:201], v[72:75]
	v_mfma_f32_16x16x32_bf16 v[68:71], v[162:165], v[220:223], v[68:71]
	v_mfma_f32_16x16x32_bf16 v[64:67], v[170:173], v[220:223], v[64:67]
	s_setprio 0
	s_barrier
	s_add_i32 s46, s46, s27
	v_lshl_add_u64 v[190:191], s[18:19], 0, v[192:193]
	s_mov_b32 m0, s46
	ds_read_b128 v[174:177], v141 offset:16384
	ds_read_b128 v[178:181], v141 offset:17408
	ds_read_b128 v[182:185], v141 offset:18432
	ds_read_b128 v[186:189], v141 offset:19456
	ds_read_b128 v[194:197], v141 offset:20480
	ds_read_b128 v[198:201], v141 offset:21504
	ds_read_b128 v[202:205], v141 offset:22528
	ds_read_b128 v[220:223], v141 offset:23552
	global_load_lds_dwordx4 v[190:191], off
	s_add_i32 m0, s46, 0x2000
	s_add_u32 s46, s18, 0x40000
	v_lshl_add_u64 v[224:225], s[18:19], 0, v[132:133]
	s_addc_u32 s47, s19, 0
	s_add_i32 s48, s48, s27
	global_load_lds_dwordx4 v[224:225], off
	v_lshl_add_u64 v[226:227], s[46:47], 0, v[192:193]
	s_mov_b32 m0, s48
	v_lshl_add_u64 v[228:229], s[20:21], 0, v[130:131]
	global_load_lds_dwordx4 v[226:227], off
	v_lshl_add_u64 v[226:227], s[46:47], 0, v[132:133]
	s_add_i32 m0, s48, 0x2000
	s_nop 0
	global_load_lds_dwordx4 v[226:227], off
	v_lshl_add_u64 v[226:227], s[20:21], 0, v[128:129]
	s_mov_b32 m0, s28
	s_nop 0
	global_load_lds_dwordx4 v[226:227], off
	s_mov_b32 m0, s29
	s_nop 0
	global_load_lds_dwordx4 v[228:229], off
	s_waitcnt vmcnt(8)
	s_waitcnt lgkmcnt(0)
	s_barrier
	s_setprio 1
	v_mfma_f32_16x16x32_bf16 v[60:63], v[142:145], v[174:177], v[60:63]
	v_mfma_f32_16x16x32_bf16 v[56:59], v[150:153], v[174:177], v[56:59]
	v_mfma_f32_16x16x32_bf16 v[52:55], v[142:145], v[182:185], v[52:55]
	v_mfma_f32_16x16x32_bf16 v[48:51], v[150:153], v[182:185], v[48:51]
	v_mfma_f32_16x16x32_bf16 v[36:39], v[142:145], v[194:197], v[36:39]
	v_mfma_f32_16x16x32_bf16 v[32:35], v[150:153], v[194:197], v[32:35]
	v_mfma_f32_16x16x32_bf16 v[20:23], v[142:145], v[202:205], v[20:23]
	v_mfma_f32_16x16x32_bf16 v[16:19], v[150:153], v[202:205], v[16:19]
	v_mfma_f32_16x16x32_bf16 v[60:63], v[146:149], v[178:181], v[60:63]
	v_mfma_f32_16x16x32_bf16 v[56:59], v[154:157], v[178:181], v[56:59]
	v_mfma_f32_16x16x32_bf16 v[52:55], v[146:149], v[186:189], v[52:55]
	v_mfma_f32_16x16x32_bf16 v[48:51], v[154:157], v[186:189], v[48:51]
	v_mfma_f32_16x16x32_bf16 v[36:39], v[146:149], v[198:201], v[36:39]
	v_mfma_f32_16x16x32_bf16 v[32:35], v[154:157], v[198:201], v[32:35]
	v_mfma_f32_16x16x32_bf16 v[20:23], v[146:149], v[220:223], v[20:23]
	v_mfma_f32_16x16x32_bf16 v[16:19], v[154:157], v[220:223], v[16:19]
	v_mfma_f32_16x16x32_bf16 v[44:47], v[158:161], v[174:177], v[44:47]
	v_mfma_f32_16x16x32_bf16 v[40:43], v[166:169], v[174:177], v[40:43]
	v_mfma_f32_16x16x32_bf16 v[28:31], v[158:161], v[182:185], v[28:31]
	v_mfma_f32_16x16x32_bf16 v[24:27], v[166:169], v[182:185], v[24:27]
	v_mfma_f32_16x16x32_bf16 v[12:15], v[158:161], v[194:197], v[12:15]
	v_mfma_f32_16x16x32_bf16 v[8:11], v[166:169], v[194:197], v[8:11]
	v_mfma_f32_16x16x32_bf16 v[4:7], v[158:161], v[202:205], v[4:7]
	v_mfma_f32_16x16x32_bf16 v[0:3], v[166:169], v[202:205], v[0:3]
	v_mfma_f32_16x16x32_bf16 v[44:47], v[162:165], v[178:181], v[44:47]
	v_mfma_f32_16x16x32_bf16 v[40:43], v[170:173], v[178:181], v[40:43]
	v_mfma_f32_16x16x32_bf16 v[28:31], v[162:165], v[186:189], v[28:31]
	v_mfma_f32_16x16x32_bf16 v[24:27], v[170:173], v[186:189], v[24:27]
	v_mfma_f32_16x16x32_bf16 v[12:15], v[162:165], v[198:201], v[12:15]
	v_mfma_f32_16x16x32_bf16 v[8:11], v[170:173], v[198:201], v[8:11]
	v_mfma_f32_16x16x32_bf16 v[4:7], v[162:165], v[220:223], v[4:7]
	v_mfma_f32_16x16x32_bf16 v[0:3], v[170:173], v[220:223], v[0:3]
	s_setprio 0
	s_barrier
	s_add_i32 s46, 0, 0x18000
	s_add_i32 s47, 0, 0x1c000
	v_add_u32_e32 v154, s46, v140
	v_add_u32_e32 v170, s47, v140
	ds_read_b128 v[142:145], v154
	ds_read_b128 v[146:149], v154 offset:1024
	ds_read_b128 v[150:153], v154 offset:2048
	ds_read_b128 v[154:157], v154 offset:3072
	ds_read_b128 v[158:161], v170
	ds_read_b128 v[162:165], v170 offset:1024
	ds_read_b128 v[166:169], v170 offset:2048
	ds_read_b128 v[170:173], v170 offset:3072
	s_add_u32 s20, s20, 0x40000
	s_addc_u32 s21, s21, 0
	s_mov_b32 m0, s30
	v_lshl_add_u64 v[230:231], s[20:21], 0, v[128:129]
	ds_read_b128 v[174:177], v141 offset:32768
	ds_read_b128 v[178:181], v141 offset:33792
	ds_read_b128 v[182:185], v141 offset:34816
	ds_read_b128 v[186:189], v141 offset:35840
	ds_read_b128 v[194:197], v141 offset:36864
	ds_read_b128 v[198:201], v141 offset:37888
	ds_read_b128 v[202:205], v141 offset:38912
	ds_read_b128 v[220:223], v141 offset:39936
	global_load_lds_dwordx4 v[230:231], off
	v_lshl_add_u64 v[230:231], s[20:21], 0, v[130:131]
	s_mov_b32 m0, s31
	s_nop 0
	global_load_lds_dwordx4 v[230:231], off
	s_waitcnt vmcnt(8)
	s_waitcnt lgkmcnt(0)
	s_barrier
	s_setprio 1
	v_mfma_f32_16x16x32_bf16 v[124:127], v[142:145], v[174:177], v[124:127]
	v_mfma_f32_16x16x32_bf16 v[120:123], v[150:153], v[174:177], v[120:123]
	v_mfma_f32_16x16x32_bf16 v[116:119], v[142:145], v[182:185], v[116:119]
	v_mfma_f32_16x16x32_bf16 v[112:115], v[150:153], v[182:185], v[112:115]
	v_mfma_f32_16x16x32_bf16 v[100:103], v[142:145], v[194:197], v[100:103]
	v_mfma_f32_16x16x32_bf16 v[96:99], v[150:153], v[194:197], v[96:99]
	v_mfma_f32_16x16x32_bf16 v[84:87], v[142:145], v[202:205], v[84:87]
	v_mfma_f32_16x16x32_bf16 v[80:83], v[150:153], v[202:205], v[80:83]
	v_mfma_f32_16x16x32_bf16 v[124:127], v[146:149], v[178:181], v[124:127]
	v_mfma_f32_16x16x32_bf16 v[120:123], v[154:157], v[178:181], v[120:123]
	v_mfma_f32_16x16x32_bf16 v[116:119], v[146:149], v[186:189], v[116:119]
	v_mfma_f32_16x16x32_bf16 v[112:115], v[154:157], v[186:189], v[112:115]
	v_mfma_f32_16x16x32_bf16 v[100:103], v[146:149], v[198:201], v[100:103]
	v_mfma_f32_16x16x32_bf16 v[96:99], v[154:157], v[198:201], v[96:99]
	v_mfma_f32_16x16x32_bf16 v[84:87], v[146:149], v[220:223], v[84:87]
	v_mfma_f32_16x16x32_bf16 v[80:83], v[154:157], v[220:223], v[80:83]
	v_mfma_f32_16x16x32_bf16 v[108:111], v[158:161], v[174:177], v[108:111]
	v_mfma_f32_16x16x32_bf16 v[104:107], v[166:169], v[174:177], v[104:107]
	v_mfma_f32_16x16x32_bf16 v[92:95], v[158:161], v[182:185], v[92:95]
	v_mfma_f32_16x16x32_bf16 v[88:91], v[166:169], v[182:185], v[88:91]
	v_mfma_f32_16x16x32_bf16 v[76:79], v[158:161], v[194:197], v[76:79]
	v_mfma_f32_16x16x32_bf16 v[72:75], v[166:169], v[194:197], v[72:75]
	v_mfma_f32_16x16x32_bf16 v[68:71], v[158:161], v[202:205], v[68:71]
	v_mfma_f32_16x16x32_bf16 v[64:67], v[166:169], v[202:205], v[64:67]
	v_mfma_f32_16x16x32_bf16 v[108:111], v[162:165], v[178:181], v[108:111]
	v_mfma_f32_16x16x32_bf16 v[104:107], v[170:173], v[178:181], v[104:107]
	v_mfma_f32_16x16x32_bf16 v[92:95], v[162:165], v[186:189], v[92:95]
	v_mfma_f32_16x16x32_bf16 v[88:91], v[170:173], v[186:189], v[88:91]
	v_mfma_f32_16x16x32_bf16 v[76:79], v[162:165], v[198:201], v[76:79]
	v_mfma_f32_16x16x32_bf16 v[72:75], v[170:173], v[198:201], v[72:75]
	v_mfma_f32_16x16x32_bf16 v[68:71], v[162:165], v[220:223], v[68:71]
	v_mfma_f32_16x16x32_bf16 v[64:67], v[170:173], v[220:223], v[64:67]
	s_setprio 0
	s_barrier
	s_add_i32 s20, s46, s27
	v_lshl_add_u64 v[190:191], v[190:191], 0, s[76:77]
	s_mov_b32 m0, s20
	ds_read_b128 v[174:177], v141 offset:49152
	ds_read_b128 v[178:181], v141 offset:50176
	ds_read_b128 v[182:185], v141 offset:51200
	ds_read_b128 v[186:189], v141 offset:52224
	ds_read_b128 v[194:197], v141 offset:53248
	ds_read_b128 v[198:201], v141 offset:54272
	ds_read_b128 v[202:205], v141 offset:55296
	ds_read_b128 v[220:223], v141 offset:56320
	global_load_lds_dwordx4 v[190:191], off
	s_add_i32 m0, s20, 0x2000
	s_add_u32 s18, s18, 0x40080
	v_lshl_add_u64 v[190:191], v[224:225], 0, s[76:77]
	s_addc_u32 s19, s19, 0
	s_add_i32 s20, s47, s27
	global_load_lds_dwordx4 v[190:191], off
	v_lshl_add_u64 v[190:191], s[18:19], 0, v[192:193]
	s_mov_b32 m0, s20
	s_nop 0
	global_load_lds_dwordx4 v[190:191], off
	v_lshl_add_u64 v[190:191], s[18:19], 0, v[132:133]
	s_add_i32 m0, s20, 0x2000
	s_nop 0
	global_load_lds_dwordx4 v[190:191], off
	v_lshl_add_u64 v[190:191], v[226:227], 0, s[76:77]
	s_mov_b32 m0, s36
	s_nop 0
	global_load_lds_dwordx4 v[190:191], off
	v_lshl_add_u64 v[190:191], v[228:229], 0, s[76:77]
	s_mov_b32 m0, s37
	s_nop 0
	global_load_lds_dwordx4 v[190:191], off
	s_waitcnt vmcnt(8)
	s_waitcnt lgkmcnt(0)
	s_barrier
	s_setprio 1
	v_mfma_f32_16x16x32_bf16 v[60:63], v[142:145], v[174:177], v[60:63]
	v_mfma_f32_16x16x32_bf16 v[56:59], v[150:153], v[174:177], v[56:59]
	v_mfma_f32_16x16x32_bf16 v[52:55], v[142:145], v[182:185], v[52:55]
	v_mfma_f32_16x16x32_bf16 v[48:51], v[150:153], v[182:185], v[48:51]
	v_mfma_f32_16x16x32_bf16 v[36:39], v[142:145], v[194:197], v[36:39]
	v_mfma_f32_16x16x32_bf16 v[32:35], v[150:153], v[194:197], v[32:35]
	v_mfma_f32_16x16x32_bf16 v[20:23], v[142:145], v[202:205], v[20:23]
	v_mfma_f32_16x16x32_bf16 v[16:19], v[150:153], v[202:205], v[16:19]
	v_mfma_f32_16x16x32_bf16 v[60:63], v[146:149], v[178:181], v[60:63]
	v_mfma_f32_16x16x32_bf16 v[56:59], v[154:157], v[178:181], v[56:59]
	v_mfma_f32_16x16x32_bf16 v[52:55], v[146:149], v[186:189], v[52:55]
	v_mfma_f32_16x16x32_bf16 v[48:51], v[154:157], v[186:189], v[48:51]
	v_mfma_f32_16x16x32_bf16 v[36:39], v[146:149], v[198:201], v[36:39]
	v_mfma_f32_16x16x32_bf16 v[32:35], v[154:157], v[198:201], v[32:35]
	v_mfma_f32_16x16x32_bf16 v[20:23], v[146:149], v[220:223], v[20:23]
	v_mfma_f32_16x16x32_bf16 v[16:19], v[154:157], v[220:223], v[16:19]
	v_mfma_f32_16x16x32_bf16 v[44:47], v[158:161], v[174:177], v[44:47]
	v_mfma_f32_16x16x32_bf16 v[40:43], v[166:169], v[174:177], v[40:43]
	v_mfma_f32_16x16x32_bf16 v[28:31], v[158:161], v[182:185], v[28:31]
	v_mfma_f32_16x16x32_bf16 v[24:27], v[166:169], v[182:185], v[24:27]
	v_mfma_f32_16x16x32_bf16 v[12:15], v[158:161], v[194:197], v[12:15]
	v_mfma_f32_16x16x32_bf16 v[8:11], v[166:169], v[194:197], v[8:11]
	v_mfma_f32_16x16x32_bf16 v[4:7], v[158:161], v[202:205], v[4:7]
	v_mfma_f32_16x16x32_bf16 v[0:3], v[166:169], v[202:205], v[0:3]
	v_mfma_f32_16x16x32_bf16 v[44:47], v[162:165], v[178:181], v[44:47]
	v_mfma_f32_16x16x32_bf16 v[40:43], v[170:173], v[178:181], v[40:43]
	v_mfma_f32_16x16x32_bf16 v[28:31], v[162:165], v[186:189], v[28:31]
	v_mfma_f32_16x16x32_bf16 v[24:27], v[170:173], v[186:189], v[24:27]
	v_mfma_f32_16x16x32_bf16 v[12:15], v[162:165], v[198:201], v[12:15]
	v_mfma_f32_16x16x32_bf16 v[8:11], v[170:173], v[198:201], v[8:11]
	v_mfma_f32_16x16x32_bf16 v[4:7], v[162:165], v[220:223], v[4:7]
	v_mfma_f32_16x16x32_bf16 v[0:3], v[170:173], v[220:223], v[0:3]
	s_setprio 0
	s_barrier
	s_add_i32 s45, s45, 2
	s_add_u32 s43, s43, 0x100
	s_addc_u32 s44, s44, 0
	s_add_u32 s16, s16, 0x100
	s_addc_u32 s17, s17, 0
	s_cmp_gt_u32 s45, 13
	s_cbranch_scc0 .LBB0_1099
	s_and_b64 vcc, exec, s[2:3]
	s_cbranch_vccz .LBB0_1102
	s_barrier
